# GEMM main loops: trailing wave half (waves 4-7) at static priority 1, leading half at 0, no per-segment toggling
# baseline (speedup 1.0000x reference)
; __device__ __forceinline__ void xcd_barrier(const XcdBarrier& b) {
;     asm volatile("s_waitcnt vmcnt(0)" ::: "memory");
;     __syncthreads();
;     unsigned xb_z = 0u; asm volatile("" : "+v"(xb_z));
;     if (b.wv == 0 && __builtin_amdgcn_mbcnt_hi(~0u, __builtin_amdgcn_mbcnt_lo(~0u, xb_z)) == 0u) {
;         unsigned* bar = b.bar;
;         __builtin_amdgcn_s_waitcnt(0);
;         unsigned nloc = b.st[0], nx = b.st[1];
;         if (nloc == 0u) { xcd_barrier_complete(bar, b.x, nloc, nx); b.st[0] = nloc; b.st[1] = nx; }
.LBB0_119:
	v_readlane_b32 s0, v254, 30
	s_add_i32 s18, s0, 1
	s_cmp_ge_i32 s18, s83
	s_cbranch_scc1 .LBB0_171
	s_setprio 0
	s_waitcnt vmcnt(0)
	v_readlane_b32 s0, v252, 7
	v_readlane_b32 s1, v252, 8
	v_mov_b32_e32 v0, v129
	s_andn2_b64 vcc, exec, s[0:1]
	s_barrier
	s_cbranch_vccnz .LBB0_170
	v_mbcnt_lo_u32_b32 v0, -1, v0
	v_mbcnt_hi_u32_b32 v0, -1, v0
	v_cmp_eq_u32_e32 vcc, 0, v0
	s_and_saveexec_b64 s[0:1], vcc
	s_cbranch_execz .LBB0_169
	v_mov_b32_e32 v0, s84
	s_waitcnt vmcnt(0) expcnt(0) lgkmcnt(0)
	ds_read_b32 v2, v0
	ds_read_b32 v1, v0 offset:4
	s_waitcnt lgkmcnt(1)
	v_cmp_ne_u32_e32 vcc, 0, v2
	s_cbranch_vccnz .LBB0_137
	s_load_dwordx2 s[2:3], s[90:91], 0x0
	s_load_dword s6, s[90:91], 0x8
	s_mov_b32 s11, 1
	s_waitcnt lgkmcnt(0)
	s_mul_i32 s10, s3, s2
	s_mul_i32 s10, s10, s6
	s_branch .LBB0_125

; __device__ __forceinline__ void xcd_barrier(const XcdBarrier& b) {
;     asm volatile("s_waitcnt vmcnt(0)" ::: "memory");
;     __syncthreads();
;     unsigned xb_z = 0u; asm volatile("" : "+v"(xb_z));
;     if (b.wv == 0 && __builtin_amdgcn_mbcnt_hi(~0u, __builtin_amdgcn_mbcnt_lo(~0u, xb_z)) == 0u) {
;         unsigned* bar = b.bar;
;         __builtin_amdgcn_s_waitcnt(0);
;         unsigned nloc = b.st[0], nx = b.st[1];
;         if (nloc == 0u) { xcd_barrier_complete(bar, b.x, nloc, nx); b.st[0] = nloc; b.st[1] = nx; }
.LBB0_175:
	v_readlane_b32 s6, v253, 19
	v_readlane_b32 s7, v253, 20
	s_and_b64 s[2:3], s[2:3], s[6:7]
	s_and_b64 s[2:3], s[2:3], s[4:5]
	s_and_b64 s[0:1], s[0:1], s[2:3]
	s_andn2_b64 vcc, exec, s[0:1]
	s_movk_i32 s10, 0x4000
	s_cbranch_vccnz .LBB0_227
	s_setprio 0
	s_waitcnt vmcnt(0)
	v_readlane_b32 s0, v252, 7
	v_readlane_b32 s1, v252, 8
	s_waitcnt vmcnt(0)
	v_mov_b32_e32 v0, v129
	s_andn2_b64 vcc, exec, s[0:1]
	s_barrier
	s_cbranch_vccnz .LBB0_226
	v_mbcnt_lo_u32_b32 v0, -1, v0
	v_mbcnt_hi_u32_b32 v0, -1, v0
	v_cmp_eq_u32_e32 vcc, 0, v0
	s_and_saveexec_b64 s[0:1], vcc
	s_cbranch_execz .LBB0_225
	v_mov_b32_e32 v0, s84
	s_waitcnt vmcnt(0) expcnt(0) lgkmcnt(0)
	ds_read_b32 v2, v0
	ds_read_b32 v0, v0 offset:4
	s_waitcnt lgkmcnt(1)
	v_cmp_ne_u32_e32 vcc, 0, v2
	s_cbranch_vccnz .LBB0_193
	s_load_dwordx2 s[2:3], s[90:91], 0x0
	s_load_dword s4, s[90:91], 0x8
	s_mov_b32 s9, 1
	s_waitcnt lgkmcnt(0)
	s_mul_i32 s8, s3, s2
	s_mul_i32 s8, s8, s4
	s_branch .LBB0_181

; #define PG8_STAGE(bufoff, gbase, voff) do { _Pragma("unroll") for (int _i = 0; _i < 2; ++_i) \
;         __builtin_amdgcn_global_load_lds((const unsigned*)((const char*)(gbase) + (voff)[_i]), (PG8_LAS unsigned*)(lds + (bufoff) + ldsw + _i * 8192), 16, 0, 0); } while (0)
; #define PG8_LDA(dst, b, h) do { _Pragma("unroll") for (int m = 0; m < 4; ++m) _Pragma("unroll") for (int k = 0; k < 2; ++k) dst[m][k] = *(const PG8_LAS bf16x8*)(lds + PG8_SA(b, h) + aoff + m * 2048 + k * 1024); } while (0)
; #define PG8_LDB(dst, b, h) do { _Pragma("unroll") for (int n = 0; n < 2; ++n) _Pragma("unroll") for (int k = 0; k < 2; ++k) dst[n][k] = *(const PG8_LAS bf16x8*)(lds + (SP2 ? PG8_SB(b, hw) + (h) * 4096 : PG8_SB(b, h)) + boff + n * 2048 + k * 1024); } while (0)
; #define PG8_WAIT_V(n) asm volatile("s_waitcnt vmcnt(" #n ")" ::: "memory")
; #define PG8_WAIT_L(n) asm volatile("s_waitcnt lgkmcnt(" #n ")" ::: "memory")
; #define PG8_BAR __builtin_amdgcn_s_barrier()
; #define PG8_SCHED __builtin_amdgcn_sched_barrier(0)
; template <class Epi, class Sched, bool ALIGN_EPI = false, bool SP2 = false, bool F8 = false>
; __device__ __forceinline__ void gemm_phase(PG8_LAS unsigned char* lds, const Gemm g, const Sched& S, const Epi& E, int wv) {
;     ...
;             const char* a1 = cA + (size_t)(t + 1) * kstep;
;             const char* a2 = last ? nA : cA + (size_t)(t + 2) * kstep; const char* b2 = last ? nB : cB + (size_t)(t + 2) * kstep;
;             const char* a3 = a2 + kstep; const char* b3 = b2 + kstep;
;             if (last && has_next) S.a_ready(nxt);
;             if constexpr (SP2) {
;             PG8_LDB(B0, 0, 0); PG8_LDB(B1, 0, 1); PG8_SCHED; PG8_LDA(At, 0, 0); PG8_STAGE(PG8_SA(1, 1), a1 + hstepA, voffA);
;             PG8_WAIT_V(8); PG8_WAIT_L(0); PG8_BAR; PG8_MMA(0, 0, At, B0); PG8_MMA(0, 1, At, B1); PG8_BAR; PG8_SCHED;
;             PG8_LDA(At, 0, 1); PG8_STAGE(PG8_SB(0, 0), b2, voffB); PG8_STAGE(PG8_SB(0, 1), b2 + hstepB, voffB); PG8_STAGE(PG8_SA(0, 0), a2, voffA);
;             PG8_WAIT_V(8); PG8_WAIT_L(0); PG8_BAR; PG8_MMA(1, 0, At, B0); PG8_MMA(1, 1, At, B1); PG8_BAR; PG8_SCHED;
.LBB0_239:
	v_add_u32_e32 v149, s45, v146
	ds_read_b128 v[140:143], v149
	ds_read_b128 v[150:153], v149 offset:1024
	ds_read_b128 v[154:157], v149 offset:2048
	ds_read_b128 v[158:161], v149 offset:3072
	v_add_u32_e32 v149, s46, v146
	ds_read_b128 v[162:165], v149
	ds_read_b128 v[166:169], v149 offset:1024
	ds_read_b128 v[170:173], v149 offset:2048
	ds_read_b128 v[174:177], v149 offset:3072
	s_add_u32 s22, s20, 0xfff80080
	s_addc_u32 s23, s21, -1
	s_cmp_eq_u32 s61, 28
	s_cselect_b32 s25, s15, s23
	s_cselect_b32 s24, s57, s22
	s_cselect_b32 s23, s13, s60
	s_cselect_b32 s22, s58, s59
	v_lshl_add_u64 v[208:209], s[20:21], 0, v[136:137]
	s_add_i32 m0, s29, 0xc000
	ds_read_b128 v[178:181], v148
	ds_read_b128 v[182:185], v148 offset:1024
	ds_read_b128 v[186:189], v148 offset:2048
	ds_read_b128 v[190:193], v148 offset:3072
	ds_read_b128 v[194:197], v148 offset:4096
	ds_read_b128 v[198:201], v148 offset:5120
	ds_read_b128 v[202:205], v148 offset:6144
	ds_read_b128 v[214:217], v148 offset:7168
	global_load_lds_dwordx4 v[208:209], off
	v_lshl_add_u64 v[208:209], s[20:21], 0, v[138:139]
	s_add_i32 m0, s29, 0xe000
	s_nop 0
	global_load_lds_dwordx4 v[208:209], off
	s_waitcnt vmcnt(8)
	s_waitcnt lgkmcnt(0)
	s_barrier
	s_cmp_lt_u32 s88, 4
	s_cbranch_scc1 .Lprio_lead_1
	s_setprio 1
.Lprio_lead_1:
	s_waitcnt lgkmcnt(0)
	v_mfma_f32_16x16x32_bf16 v[124:127], v[140:143], v[178:181], v[124:127]
	v_mfma_f32_16x16x32_bf16 v[120:123], v[154:157], v[178:181], v[120:123]
	v_mfma_f32_16x16x32_bf16 v[116:119], v[140:143], v[186:189], v[116:119]
	v_mfma_f32_16x16x32_bf16 v[108:111], v[154:157], v[186:189], v[108:111]
	v_mfma_f32_16x16x32_bf16 v[100:103], v[140:143], v[194:197], v[100:103]
	v_mfma_f32_16x16x32_bf16 v[92:95], v[154:157], v[194:197], v[92:95]
	v_mfma_f32_16x16x32_bf16 v[84:87], v[140:143], v[202:205], v[84:87]
	v_mfma_f32_16x16x32_bf16 v[76:79], v[154:157], v[202:205], v[76:79]
	v_mfma_f32_16x16x32_bf16 v[124:127], v[150:153], v[182:185], v[124:127]
	v_mfma_f32_16x16x32_bf16 v[120:123], v[158:161], v[182:185], v[120:123]
	v_mfma_f32_16x16x32_bf16 v[116:119], v[150:153], v[190:193], v[116:119]
	v_mfma_f32_16x16x32_bf16 v[108:111], v[158:161], v[190:193], v[108:111]
	v_mfma_f32_16x16x32_bf16 v[100:103], v[150:153], v[198:201], v[100:103]
	v_mfma_f32_16x16x32_bf16 v[92:95], v[158:161], v[198:201], v[92:95]
	v_mfma_f32_16x16x32_bf16 v[84:87], v[150:153], v[214:217], v[84:87]
	v_mfma_f32_16x16x32_bf16 v[76:79], v[158:161], v[214:217], v[76:79]
	v_mfma_f32_16x16x32_bf16 v[112:115], v[162:165], v[178:181], v[112:115]
	v_mfma_f32_16x16x32_bf16 v[104:107], v[170:173], v[178:181], v[104:107]
	v_mfma_f32_16x16x32_bf16 v[96:99], v[162:165], v[186:189], v[96:99]
	v_mfma_f32_16x16x32_bf16 v[88:91], v[170:173], v[186:189], v[88:91]
	v_mfma_f32_16x16x32_bf16 v[80:83], v[162:165], v[194:197], v[80:83]
	v_mfma_f32_16x16x32_bf16 v[72:75], v[170:173], v[194:197], v[72:75]
	v_mfma_f32_16x16x32_bf16 v[68:71], v[162:165], v[202:205], v[68:71]
	v_mfma_f32_16x16x32_bf16 v[64:67], v[170:173], v[202:205], v[64:67]
	v_mfma_f32_16x16x32_bf16 v[112:115], v[166:169], v[182:185], v[112:115]
	v_mfma_f32_16x16x32_bf16 v[104:107], v[174:177], v[182:185], v[104:107]
	v_mfma_f32_16x16x32_bf16 v[96:99], v[166:169], v[190:193], v[96:99]
	v_mfma_f32_16x16x32_bf16 v[88:91], v[174:177], v[190:193], v[88:91]
	v_mfma_f32_16x16x32_bf16 v[80:83], v[166:169], v[198:201], v[80:83]
	v_mfma_f32_16x16x32_bf16 v[72:75], v[174:177], v[198:201], v[72:75]
	v_mfma_f32_16x16x32_bf16 v[68:71], v[166:169], v[214:217], v[68:71]
	v_mfma_f32_16x16x32_bf16 v[64:67], v[174:177], v[214:217], v[64:67]
	s_barrier
	s_mov_b32 m0, s30
	v_lshl_add_u64 v[208:209], s[22:23], 0, v[128:129]
	s_add_u32 s62, s22, 0x80000
	ds_read_b128 v[178:181], v148 offset:16384
	ds_read_b128 v[182:185], v148 offset:17408
	ds_read_b128 v[186:189], v148 offset:18432
	ds_read_b128 v[190:193], v148 offset:19456
	ds_read_b128 v[194:197], v148 offset:20480
	ds_read_b128 v[198:201], v148 offset:21504
	ds_read_b128 v[202:205], v148 offset:22528
	ds_read_b128 v[214:217], v148 offset:23552
	global_load_lds_dwordx4 v[208:209], off
	v_lshl_add_u64 v[210:211], s[22:23], 0, v[130:131]
	s_mov_b32 m0, s31
	s_addc_u32 s63, s23, 0
	global_load_lds_dwordx4 v[210:211], off
	v_lshl_add_u64 v[218:219], s[62:63], 0, v[128:129]
	s_mov_b32 m0, s34
	v_lshl_add_u64 v[220:221], s[24:25], 0, v[132:133]
	global_load_lds_dwordx4 v[218:219], off
	v_lshl_add_u64 v[218:219], s[62:63], 0, v[130:131]
	s_mov_b32 m0, s35
	s_nop 0
	global_load_lds_dwordx4 v[218:219], off
	v_lshl_add_u64 v[218:219], s[24:25], 0, v[134:135]
	s_mov_b32 m0, s29
	s_nop 0
	global_load_lds_dwordx4 v[218:219], off
	s_mov_b32 m0, s36
	s_nop 0
	global_load_lds_dwordx4 v[220:221], off
	s_waitcnt vmcnt(8)
	s_waitcnt lgkmcnt(0)
	s_barrier
; #define PG8_STAGE(bufoff, gbase, voff) do { _Pragma("unroll") for (int _i = 0; _i < 2; ++_i) \
;         __builtin_amdgcn_global_load_lds((const unsigned*)((const char*)(gbase) + (voff)[_i]), (PG8_LAS unsigned*)(lds + (bufoff) + ldsw + _i * 8192), 16, 0, 0); } while (0)
; #define PG8_LDA(dst, b, h) do { _Pragma("unroll") for (int m = 0; m < 4; ++m) _Pragma("unroll") for (int k = 0; k < 2; ++k) dst[m][k] = *(const PG8_LAS bf16x8*)(lds + PG8_SA(b, h) + aoff + m * 2048 + k * 1024); } while (0)
; #define PG8_LDB(dst, b, h) do { _Pragma("unroll") for (int n = 0; n < 2; ++n) _Pragma("unroll") for (int k = 0; k < 2; ++k) dst[n][k] = *(const PG8_LAS bf16x8*)(lds + (SP2 ? PG8_SB(b, hw) + (h) * 4096 : PG8_SB(b, h)) + boff + n * 2048 + k * 1024); } while (0)
; #define PG8_WAIT_V(n) asm volatile("s_waitcnt vmcnt(" #n ")" ::: "memory")
; #define PG8_WAIT_L(n) asm volatile("s_waitcnt lgkmcnt(" #n ")" ::: "memory")
; #define PG8_BAR __builtin_amdgcn_s_barrier()
; #define PG8_SCHED __builtin_amdgcn_sched_barrier(0)
; template <class Epi, class Sched, bool ALIGN_EPI = false, bool SP2 = false, bool F8 = false>
; __device__ __forceinline__ void gemm_phase(PG8_LAS unsigned char* lds, const Gemm g, const Sched& S, const Epi& E, int wv) {
;     ...
;             PG8_WAIT_V(8); PG8_WAIT_L(0); PG8_BAR; PG8_MMA(1, 0, At, B0); PG8_MMA(1, 1, At, B1); PG8_BAR; PG8_SCHED;
;             PG8_LDB(B0, 1, 0); PG8_LDB(B1, 1, 1); PG8_SCHED; PG8_LDA(At, 1, 0); PG8_STAGE(PG8_SA(0, 1), a2 + hstepA, voffA);
;             PG8_WAIT_V(8); PG8_WAIT_L(0); PG8_BAR; PG8_MMA(0, 0, At, B0); PG8_MMA(0, 1, At, B1); PG8_BAR; PG8_SCHED;
	s_waitcnt lgkmcnt(0)
	v_mfma_f32_16x16x32_bf16 v[60:63], v[140:143], v[178:181], v[60:63]
	v_mfma_f32_16x16x32_bf16 v[56:59], v[154:157], v[178:181], v[56:59]
	v_mfma_f32_16x16x32_bf16 v[52:55], v[140:143], v[186:189], v[52:55]
	v_mfma_f32_16x16x32_bf16 v[44:47], v[154:157], v[186:189], v[44:47]
	v_mfma_f32_16x16x32_bf16 v[36:39], v[140:143], v[194:197], v[36:39]
	v_mfma_f32_16x16x32_bf16 v[28:31], v[154:157], v[194:197], v[28:31]
	v_mfma_f32_16x16x32_bf16 v[20:23], v[140:143], v[202:205], v[20:23]
	v_mfma_f32_16x16x32_bf16 v[12:15], v[154:157], v[202:205], v[12:15]
	v_mfma_f32_16x16x32_bf16 v[60:63], v[150:153], v[182:185], v[60:63]
	v_mfma_f32_16x16x32_bf16 v[56:59], v[158:161], v[182:185], v[56:59]
	v_mfma_f32_16x16x32_bf16 v[52:55], v[150:153], v[190:193], v[52:55]
	v_mfma_f32_16x16x32_bf16 v[44:47], v[158:161], v[190:193], v[44:47]
	v_mfma_f32_16x16x32_bf16 v[36:39], v[150:153], v[198:201], v[36:39]
	v_mfma_f32_16x16x32_bf16 v[28:31], v[158:161], v[198:201], v[28:31]
	v_mfma_f32_16x16x32_bf16 v[20:23], v[150:153], v[214:217], v[20:23]
	v_mfma_f32_16x16x32_bf16 v[12:15], v[158:161], v[214:217], v[12:15]
	v_mfma_f32_16x16x32_bf16 v[48:51], v[162:165], v[178:181], v[48:51]
	v_mfma_f32_16x16x32_bf16 v[40:43], v[170:173], v[178:181], v[40:43]
	v_mfma_f32_16x16x32_bf16 v[32:35], v[162:165], v[186:189], v[32:35]
	v_mfma_f32_16x16x32_bf16 v[24:27], v[170:173], v[186:189], v[24:27]
	v_mfma_f32_16x16x32_bf16 v[16:19], v[162:165], v[194:197], v[16:19]
	v_mfma_f32_16x16x32_bf16 v[8:11], v[170:173], v[194:197], v[8:11]
	v_mfma_f32_16x16x32_bf16 v[4:7], v[162:165], v[202:205], v[4:7]
	v_mfma_f32_16x16x32_bf16 v[0:3], v[170:173], v[202:205], v[0:3]
	v_mfma_f32_16x16x32_bf16 v[48:51], v[166:169], v[182:185], v[48:51]
	v_mfma_f32_16x16x32_bf16 v[40:43], v[174:177], v[182:185], v[40:43]
	v_mfma_f32_16x16x32_bf16 v[32:35], v[166:169], v[190:193], v[32:35]
	v_mfma_f32_16x16x32_bf16 v[24:27], v[174:177], v[190:193], v[24:27]
	v_mfma_f32_16x16x32_bf16 v[16:19], v[166:169], v[198:201], v[16:19]
	v_mfma_f32_16x16x32_bf16 v[8:11], v[174:177], v[198:201], v[8:11]
	v_mfma_f32_16x16x32_bf16 v[4:7], v[166:169], v[214:217], v[4:7]
	v_mfma_f32_16x16x32_bf16 v[0:3], v[174:177], v[214:217], v[0:3]
	s_barrier
	v_add_u32_e32 v149, s47, v146
	ds_read_b128 v[140:143], v149
	ds_read_b128 v[150:153], v149 offset:1024
	ds_read_b128 v[154:157], v149 offset:2048
	ds_read_b128 v[158:161], v149 offset:3072
	v_add_u32_e32 v149, s48, v146
	ds_read_b128 v[162:165], v149
	ds_read_b128 v[166:169], v149 offset:1024
	ds_read_b128 v[170:173], v149 offset:2048
	ds_read_b128 v[174:177], v149 offset:3072
	s_add_u32 s24, s24, 0x80000
	s_addc_u32 s25, s25, 0
	s_mov_b32 m0, s37
	v_lshl_add_u64 v[222:223], s[24:25], 0, v[134:135]
	ds_read_b128 v[178:181], v148 offset:32768
	ds_read_b128 v[182:185], v148 offset:33792
	ds_read_b128 v[186:189], v148 offset:34816
	ds_read_b128 v[190:193], v148 offset:35840
	ds_read_b128 v[194:197], v148 offset:36864
	ds_read_b128 v[198:201], v148 offset:37888
	ds_read_b128 v[202:205], v148 offset:38912
	ds_read_b128 v[214:217], v148 offset:39936
	global_load_lds_dwordx4 v[222:223], off
	v_lshl_add_u64 v[222:223], s[24:25], 0, v[132:133]
	s_mov_b32 m0, s38
	s_nop 0
	global_load_lds_dwordx4 v[222:223], off
	s_waitcnt vmcnt(8)
	s_waitcnt lgkmcnt(0)
	s_barrier
	s_waitcnt lgkmcnt(0)
	v_mfma_f32_16x16x32_bf16 v[124:127], v[140:143], v[178:181], v[124:127]
	v_mfma_f32_16x16x32_bf16 v[120:123], v[154:157], v[178:181], v[120:123]
	v_mfma_f32_16x16x32_bf16 v[116:119], v[140:143], v[186:189], v[116:119]
	v_mfma_f32_16x16x32_bf16 v[108:111], v[154:157], v[186:189], v[108:111]
	v_mfma_f32_16x16x32_bf16 v[100:103], v[140:143], v[194:197], v[100:103]
	v_mfma_f32_16x16x32_bf16 v[92:95], v[154:157], v[194:197], v[92:95]
	v_mfma_f32_16x16x32_bf16 v[84:87], v[140:143], v[202:205], v[84:87]
	v_mfma_f32_16x16x32_bf16 v[76:79], v[154:157], v[202:205], v[76:79]
	v_mfma_f32_16x16x32_bf16 v[124:127], v[150:153], v[182:185], v[124:127]
	v_mfma_f32_16x16x32_bf16 v[120:123], v[158:161], v[182:185], v[120:123]
	v_mfma_f32_16x16x32_bf16 v[116:119], v[150:153], v[190:193], v[116:119]
	v_mfma_f32_16x16x32_bf16 v[108:111], v[158:161], v[190:193], v[108:111]
	v_mfma_f32_16x16x32_bf16 v[100:103], v[150:153], v[198:201], v[100:103]
	v_mfma_f32_16x16x32_bf16 v[92:95], v[158:161], v[198:201], v[92:95]
	v_mfma_f32_16x16x32_bf16 v[84:87], v[150:153], v[214:217], v[84:87]
	v_mfma_f32_16x16x32_bf16 v[76:79], v[158:161], v[214:217], v[76:79]
	v_mfma_f32_16x16x32_bf16 v[112:115], v[162:165], v[178:181], v[112:115]
	v_mfma_f32_16x16x32_bf16 v[104:107], v[170:173], v[178:181], v[104:107]
	v_mfma_f32_16x16x32_bf16 v[96:99], v[162:165], v[186:189], v[96:99]
	v_mfma_f32_16x16x32_bf16 v[88:91], v[170:173], v[186:189], v[88:91]
	v_mfma_f32_16x16x32_bf16 v[80:83], v[162:165], v[194:197], v[80:83]
	v_mfma_f32_16x16x32_bf16 v[72:75], v[170:173], v[194:197], v[72:75]
	v_mfma_f32_16x16x32_bf16 v[68:71], v[162:165], v[202:205], v[68:71]
	v_mfma_f32_16x16x32_bf16 v[64:67], v[170:173], v[202:205], v[64:67]
	v_mfma_f32_16x16x32_bf16 v[112:115], v[166:169], v[182:185], v[112:115]
	v_mfma_f32_16x16x32_bf16 v[104:107], v[174:177], v[182:185], v[104:107]
	v_mfma_f32_16x16x32_bf16 v[96:99], v[166:169], v[190:193], v[96:99]
	v_mfma_f32_16x16x32_bf16 v[88:91], v[174:177], v[190:193], v[88:91]
	v_mfma_f32_16x16x32_bf16 v[80:83], v[166:169], v[198:201], v[80:83]
	v_mfma_f32_16x16x32_bf16 v[72:75], v[174:177], v[198:201], v[72:75]
	v_mfma_f32_16x16x32_bf16 v[68:71], v[166:169], v[214:217], v[68:71]
	v_mfma_f32_16x16x32_bf16 v[64:67], v[174:177], v[214:217], v[64:67]
	s_barrier
; #define PG8_STAGE(bufoff, gbase, voff) do { _Pragma("unroll") for (int _i = 0; _i < 2; ++_i) \
;         __builtin_amdgcn_global_load_lds((const unsigned*)((const char*)(gbase) + (voff)[_i]), (PG8_LAS unsigned*)(lds + (bufoff) + ldsw + _i * 8192), 16, 0, 0); } while (0)
; #define PG8_LDA(dst, b, h) do { _Pragma("unroll") for (int m = 0; m < 4; ++m) _Pragma("unroll") for (int k = 0; k < 2; ++k) dst[m][k] = *(const PG8_LAS bf16x8*)(lds + PG8_SA(b, h) + aoff + m * 2048 + k * 1024); } while (0)
; #define PG8_WAIT_V(n) asm volatile("s_waitcnt vmcnt(" #n ")" ::: "memory")
; #define PG8_WAIT_L(n) asm volatile("s_waitcnt lgkmcnt(" #n ")" ::: "memory")
; #define PG8_BAR __builtin_amdgcn_s_barrier()
; #define PG8_SCHED __builtin_amdgcn_sched_barrier(0)
; template <class Epi, class Sched, bool ALIGN_EPI = false, bool SP2 = false, bool F8 = false>
; __device__ __forceinline__ void gemm_phase(PG8_LAS unsigned char* lds, const Gemm g, const Sched& S, const Epi& E, int wv) {
;     ...
;             PG8_LDA(At, 1, 1); PG8_STAGE(PG8_SB(1, 0), b3, voffB); PG8_STAGE(PG8_SB(1, 1), b3 + hstepB, voffB); PG8_STAGE(PG8_SA(1, 0), a3, voffA);
;             PG8_WAIT_V(8); PG8_WAIT_L(0); PG8_BAR; PG8_MMA(1, 0, At, B0); PG8_MMA(1, 1, At, B1); PG8_BAR; PG8_SCHED;
	s_mov_b32 m0, s39
	v_lshl_add_u64 v[208:209], v[208:209], 0, s[52:53]
	s_add_u32 s22, s22, 0x80080
	ds_read_b128 v[178:181], v148 offset:49152
	ds_read_b128 v[182:185], v148 offset:50176
	ds_read_b128 v[186:189], v148 offset:51200
	ds_read_b128 v[190:193], v148 offset:52224
	ds_read_b128 v[194:197], v148 offset:53248
	ds_read_b128 v[198:201], v148 offset:54272
	ds_read_b128 v[202:205], v148 offset:55296
	ds_read_b128 v[214:217], v148 offset:56320
	global_load_lds_dwordx4 v[208:209], off
	v_lshl_add_u64 v[208:209], v[210:211], 0, s[52:53]
	s_mov_b32 m0, s40
	s_addc_u32 s23, s23, 0
	global_load_lds_dwordx4 v[208:209], off
	v_lshl_add_u64 v[208:209], s[22:23], 0, v[128:129]
	s_mov_b32 m0, s43
	s_nop 0
	global_load_lds_dwordx4 v[208:209], off
	v_lshl_add_u64 v[208:209], s[22:23], 0, v[130:131]
	s_mov_b32 m0, s44
	s_nop 0
	global_load_lds_dwordx4 v[208:209], off
	v_lshl_add_u64 v[208:209], v[218:219], 0, s[52:53]
	s_mov_b32 m0, s41
	s_nop 0
	global_load_lds_dwordx4 v[208:209], off
	v_lshl_add_u64 v[208:209], v[220:221], 0, s[52:53]
	s_mov_b32 m0, s42
	s_nop 0
	global_load_lds_dwordx4 v[208:209], off
	s_waitcnt vmcnt(8)
	s_waitcnt lgkmcnt(0)
	s_barrier
	s_waitcnt lgkmcnt(0)
	v_mfma_f32_16x16x32_bf16 v[60:63], v[140:143], v[178:181], v[60:63]
	v_mfma_f32_16x16x32_bf16 v[56:59], v[154:157], v[178:181], v[56:59]
	v_mfma_f32_16x16x32_bf16 v[52:55], v[140:143], v[186:189], v[52:55]
	v_mfma_f32_16x16x32_bf16 v[44:47], v[154:157], v[186:189], v[44:47]
	v_mfma_f32_16x16x32_bf16 v[36:39], v[140:143], v[194:197], v[36:39]
	v_mfma_f32_16x16x32_bf16 v[28:31], v[154:157], v[194:197], v[28:31]
	v_mfma_f32_16x16x32_bf16 v[20:23], v[140:143], v[202:205], v[20:23]
	v_mfma_f32_16x16x32_bf16 v[12:15], v[154:157], v[202:205], v[12:15]
	v_mfma_f32_16x16x32_bf16 v[60:63], v[150:153], v[182:185], v[60:63]
	v_mfma_f32_16x16x32_bf16 v[56:59], v[158:161], v[182:185], v[56:59]
	v_mfma_f32_16x16x32_bf16 v[52:55], v[150:153], v[190:193], v[52:55]
	v_mfma_f32_16x16x32_bf16 v[44:47], v[158:161], v[190:193], v[44:47]
	v_mfma_f32_16x16x32_bf16 v[36:39], v[150:153], v[198:201], v[36:39]
	v_mfma_f32_16x16x32_bf16 v[28:31], v[158:161], v[198:201], v[28:31]
	v_mfma_f32_16x16x32_bf16 v[20:23], v[150:153], v[214:217], v[20:23]
	v_mfma_f32_16x16x32_bf16 v[12:15], v[158:161], v[214:217], v[12:15]
	v_mfma_f32_16x16x32_bf16 v[48:51], v[162:165], v[178:181], v[48:51]
	v_mfma_f32_16x16x32_bf16 v[40:43], v[170:173], v[178:181], v[40:43]
	v_mfma_f32_16x16x32_bf16 v[32:35], v[162:165], v[186:189], v[32:35]
	v_mfma_f32_16x16x32_bf16 v[24:27], v[170:173], v[186:189], v[24:27]
	v_mfma_f32_16x16x32_bf16 v[16:19], v[162:165], v[194:197], v[16:19]
	v_mfma_f32_16x16x32_bf16 v[8:11], v[170:173], v[194:197], v[8:11]
	v_mfma_f32_16x16x32_bf16 v[4:7], v[162:165], v[202:205], v[4:7]
	v_mfma_f32_16x16x32_bf16 v[0:3], v[170:173], v[202:205], v[0:3]
	v_mfma_f32_16x16x32_bf16 v[48:51], v[166:169], v[182:185], v[48:51]
	v_mfma_f32_16x16x32_bf16 v[40:43], v[174:177], v[182:185], v[40:43]
	v_mfma_f32_16x16x32_bf16 v[32:35], v[166:169], v[190:193], v[32:35]
	v_mfma_f32_16x16x32_bf16 v[24:27], v[174:177], v[190:193], v[24:27]
	v_mfma_f32_16x16x32_bf16 v[16:19], v[166:169], v[198:201], v[16:19]
	v_mfma_f32_16x16x32_bf16 v[8:11], v[174:177], v[198:201], v[8:11]
	v_mfma_f32_16x16x32_bf16 v[4:7], v[166:169], v[214:217], v[4:7]
	v_mfma_f32_16x16x32_bf16 v[0:3], v[174:177], v[214:217], v[0:3]
	s_barrier
	s_add_i32 s61, s61, 2
	s_add_u32 s20, s20, 0x100
	s_addc_u32 s21, s21, 0
	s_add_u32 s59, s59, 0x100
	s_addc_u32 s60, s60, 0
	s_cmp_gt_u32 s61, 29
	s_cbranch_scc0 .LBB0_239
	s_and_b64 vcc, exec, s[10:11]
	s_cbranch_vccz .LBB0_242
	s_barrier

; #define PG8_STAGE(bufoff, gbase, voff) do { _Pragma("unroll") for (int _i = 0; _i < 2; ++_i) \
;         __builtin_amdgcn_global_load_lds((const unsigned*)((const char*)(gbase) + (voff)[_i]), (PG8_LAS unsigned*)(lds + (bufoff) + ldsw + _i * 8192), 16, 0, 0); } while (0)
; #define PG8_LDA(dst, b, h) do { _Pragma("unroll") for (int m = 0; m < 4; ++m) _Pragma("unroll") for (int k = 0; k < 2; ++k) dst[m][k] = *(const PG8_LAS bf16x8*)(lds + PG8_SA(b, h) + aoff + m * 2048 + k * 1024); } while (0)
; #define PG8_LDB(dst, b, h) do { _Pragma("unroll") for (int n = 0; n < 2; ++n) _Pragma("unroll") for (int k = 0; k < 2; ++k) dst[n][k] = *(const PG8_LAS bf16x8*)(lds + (SP2 ? PG8_SB(b, hw) + (h) * 4096 : PG8_SB(b, h)) + boff + n * 2048 + k * 1024); } while (0)
; #define PG8_WAIT_V(n) asm volatile("s_waitcnt vmcnt(" #n ")" ::: "memory")
; #define PG8_WAIT_L(n) asm volatile("s_waitcnt lgkmcnt(" #n ")" ::: "memory")
; #define PG8_BAR __builtin_amdgcn_s_barrier()
; #define PG8_SCHED __builtin_amdgcn_sched_barrier(0)
; template <class Epi, class Sched, bool ALIGN_EPI = false, bool SP2 = false, bool F8 = false>
; __device__ __forceinline__ void gemm_phase(PG8_LAS unsigned char* lds, const Gemm g, const Sched& S, const Epi& E, int wv) {
;     ...
;             const char* a1 = cA + (size_t)(t + 1) * kstep;
;             const char* a2 = last ? nA : cA + (size_t)(t + 2) * kstep; const char* b2 = last ? nB : cB + (size_t)(t + 2) * kstep;
;             const char* a3 = a2 + kstep; const char* b3 = b2 + kstep;
;             if (last && has_next) S.a_ready(nxt);
;             if constexpr (SP2) {
;             PG8_LDB(B0, 0, 0); PG8_LDB(B1, 0, 1); PG8_SCHED; PG8_LDA(At, 0, 0); PG8_STAGE(PG8_SA(1, 1), a1 + hstepA, voffA);
;             PG8_WAIT_V(8); PG8_WAIT_L(0); PG8_BAR; PG8_MMA(0, 0, At, B0); PG8_MMA(0, 1, At, B1); PG8_BAR; PG8_SCHED;
;             PG8_LDA(At, 0, 1); PG8_STAGE(PG8_SB(0, 0), b2, voffB); PG8_STAGE(PG8_SB(0, 1), b2 + hstepB, voffB); PG8_STAGE(PG8_SA(0, 0), a2, voffA);
;             PG8_WAIT_V(8); PG8_WAIT_L(0); PG8_BAR; PG8_MMA(1, 0, At, B0); PG8_MMA(1, 1, At, B1); PG8_BAR; PG8_SCHED;
.LBB0_286:
	v_add_u32_e32 v0, s59, v181
	v_add_u32_e32 v4, s60, v181
	ds_read_b128 v[24:27], v0
	ds_read_b128 v[28:31], v0 offset:1024
	ds_read_b128 v[16:19], v0 offset:2048
	ds_read_b128 v[20:23], v0 offset:3072
	ds_read_b128 v[8:11], v4
	ds_read_b128 v[12:15], v4 offset:1024
	ds_read_b128 v[0:3], v4 offset:2048
	ds_read_b128 v[4:7], v4 offset:3072
	s_add_u32 s28, s26, 0xfffc0080
	s_addc_u32 s29, s27, -1
	s_cmp_eq_u32 s71, 12
	s_cselect_b32 s31, s13, s29
	s_cselect_b32 s30, s17, s28
	s_cselect_b32 s29, s15, s70
	s_cselect_b32 s28, s67, s69
	v_lshl_add_u64 v[200:201], s[26:27], 0, v[168:169]
	s_add_i32 m0, s19, 0xc000
	ds_read_b128 v[172:175], v183
	ds_read_b128 v[176:179], v183 offset:1024
	ds_read_b128 v[184:187], v183 offset:2048
	ds_read_b128 v[188:191], v183 offset:3072
	ds_read_b128 v[192:195], v183 offset:4096
	ds_read_b128 v[196:199], v183 offset:5120
	ds_read_b128 v[214:217], v183 offset:6144
	ds_read_b128 v[218:221], v183 offset:7168
	global_load_lds_dwordx4 v[200:201], off
	v_lshl_add_u64 v[200:201], s[26:27], 0, v[170:171]
	s_add_i32 m0, s19, 0xe000
	s_nop 0
	global_load_lds_dwordx4 v[200:201], off
	s_waitcnt vmcnt(8)
	s_waitcnt lgkmcnt(0)
	s_barrier
	s_cmp_lt_u32 s88, 4
	s_cbranch_scc1 .Lprio_lead_2
	s_setprio 1
.Lprio_lead_2:
	s_waitcnt lgkmcnt(0)
	v_mfma_f32_16x16x128_f8f6f4 v[158:161], v[24:31], v[172:179], v[158:161]
	v_mfma_f32_16x16x128_f8f6f4 v[154:157], v[16:23], v[172:179], v[154:157]
	v_mfma_f32_16x16x128_f8f6f4 v[146:149], v[24:31], v[184:191], v[146:149]
	v_mfma_f32_16x16x128_f8f6f4 v[138:141], v[16:23], v[184:191], v[138:141]
	v_mfma_f32_16x16x128_f8f6f4 v[130:133], v[24:31], v[192:199], v[130:133]
	v_mfma_f32_16x16x128_f8f6f4 v[120:123], v[16:23], v[192:199], v[120:123]
	v_mfma_f32_16x16x128_f8f6f4 v[112:115], v[24:31], v[214:221], v[112:115]
	v_mfma_f32_16x16x128_f8f6f4 v[104:107], v[16:23], v[214:221], v[104:107]
	v_mfma_f32_16x16x128_f8f6f4 v[150:153], v[8:15], v[172:179], v[150:153]
	v_mfma_f32_16x16x128_f8f6f4 v[142:145], v[0:7], v[172:179], v[142:145]
	v_mfma_f32_16x16x128_f8f6f4 v[134:137], v[8:15], v[184:191], v[134:137]
	v_mfma_f32_16x16x128_f8f6f4 v[124:127], v[0:7], v[184:191], v[124:127]
	v_mfma_f32_16x16x128_f8f6f4 v[116:119], v[8:15], v[192:199], v[116:119]
	v_mfma_f32_16x16x128_f8f6f4 v[108:111], v[0:7], v[192:199], v[108:111]
	v_mfma_f32_16x16x128_f8f6f4 v[100:103], v[8:15], v[214:221], v[100:103]
	v_mfma_f32_16x16x128_f8f6f4 v[96:99], v[0:7], v[214:221], v[96:99]
	s_barrier
	s_mov_b32 m0, s40
	v_lshl_add_u64 v[172:173], s[28:29], 0, v[128:129]
	s_add_u32 s72, s28, 0x40000
	ds_read_b128 v[184:187], v183 offset:16384
	ds_read_b128 v[188:191], v183 offset:17408
	ds_read_b128 v[192:195], v183 offset:18432
	ds_read_b128 v[196:199], v183 offset:19456
	ds_read_b128 v[214:217], v183 offset:20480
	ds_read_b128 v[218:221], v183 offset:21504
	ds_read_b128 v[222:225], v183 offset:22528
	ds_read_b128 v[226:229], v183 offset:23552
	global_load_lds_dwordx4 v[172:173], off
	v_lshl_add_u64 v[174:175], s[28:29], 0, v[166:167]
	s_mov_b32 m0, s41
	s_addc_u32 s73, s29, 0
	global_load_lds_dwordx4 v[174:175], off
	v_lshl_add_u64 v[176:177], s[72:73], 0, v[128:129]
	s_mov_b32 m0, s42
	v_lshl_add_u64 v[178:179], s[30:31], 0, v[164:165]
	global_load_lds_dwordx4 v[176:177], off
	v_lshl_add_u64 v[176:177], s[72:73], 0, v[166:167]
	s_mov_b32 m0, s43
	s_nop 0
	global_load_lds_dwordx4 v[176:177], off
	v_lshl_add_u64 v[176:177], s[30:31], 0, v[162:163]
	s_mov_b32 m0, s19
	s_nop 0
	global_load_lds_dwordx4 v[176:177], off
	s_mov_b32 m0, s44
	s_nop 0
	global_load_lds_dwordx4 v[178:179], off
	s_waitcnt vmcnt(8)
	s_waitcnt lgkmcnt(0)
	s_barrier
	s_waitcnt lgkmcnt(0)
	v_mfma_f32_16x16x128_f8f6f4 v[92:95], v[24:31], v[184:191], v[92:95]
	v_mfma_f32_16x16x128_f8f6f4 v[88:91], v[16:23], v[184:191], v[88:91]
	v_mfma_f32_16x16x128_f8f6f4 v[80:83], v[24:31], v[192:199], v[80:83]
	v_mfma_f32_16x16x128_f8f6f4 v[72:75], v[16:23], v[192:199], v[72:75]
	v_mfma_f32_16x16x128_f8f6f4 v[64:67], v[24:31], v[214:221], v[64:67]
	v_mfma_f32_16x16x128_f8f6f4 v[56:59], v[16:23], v[214:221], v[56:59]
	v_mfma_f32_16x16x128_f8f6f4 v[48:51], v[24:31], v[222:229], v[48:51]
	v_mfma_f32_16x16x128_f8f6f4 v[40:43], v[16:23], v[222:229], v[40:43]
	v_mfma_f32_16x16x128_f8f6f4 v[84:87], v[8:15], v[184:191], v[84:87]
	v_mfma_f32_16x16x128_f8f6f4 v[76:79], v[0:7], v[184:191], v[76:79]
	v_mfma_f32_16x16x128_f8f6f4 v[68:71], v[8:15], v[192:199], v[68:71]
	v_mfma_f32_16x16x128_f8f6f4 v[60:63], v[0:7], v[192:199], v[60:63]
	v_mfma_f32_16x16x128_f8f6f4 v[52:55], v[8:15], v[214:221], v[52:55]
	v_mfma_f32_16x16x128_f8f6f4 v[44:47], v[0:7], v[214:221], v[44:47]
	v_mfma_f32_16x16x128_f8f6f4 v[36:39], v[8:15], v[222:229], v[36:39]
	v_mfma_f32_16x16x128_f8f6f4 v[32:35], v[0:7], v[222:229], v[32:35]
	s_barrier
; #define PG8_STAGE(bufoff, gbase, voff) do { _Pragma("unroll") for (int _i = 0; _i < 2; ++_i) \
;         __builtin_amdgcn_global_load_lds((const unsigned*)((const char*)(gbase) + (voff)[_i]), (PG8_LAS unsigned*)(lds + (bufoff) + ldsw + _i * 8192), 16, 0, 0); } while (0)
; #define PG8_LDA(dst, b, h) do { _Pragma("unroll") for (int m = 0; m < 4; ++m) _Pragma("unroll") for (int k = 0; k < 2; ++k) dst[m][k] = *(const PG8_LAS bf16x8*)(lds + PG8_SA(b, h) + aoff + m * 2048 + k * 1024); } while (0)
; #define PG8_LDB(dst, b, h) do { _Pragma("unroll") for (int n = 0; n < 2; ++n) _Pragma("unroll") for (int k = 0; k < 2; ++k) dst[n][k] = *(const PG8_LAS bf16x8*)(lds + (SP2 ? PG8_SB(b, hw) + (h) * 4096 : PG8_SB(b, h)) + boff + n * 2048 + k * 1024); } while (0)
; #define PG8_WAIT_V(n) asm volatile("s_waitcnt vmcnt(" #n ")" ::: "memory")
; #define PG8_WAIT_L(n) asm volatile("s_waitcnt lgkmcnt(" #n ")" ::: "memory")
; #define PG8_BAR __builtin_amdgcn_s_barrier()
; #define PG8_SCHED __builtin_amdgcn_sched_barrier(0)
; template <class Epi, class Sched, bool ALIGN_EPI = false, bool SP2 = false, bool F8 = false>
; __device__ __forceinline__ void gemm_phase(PG8_LAS unsigned char* lds, const Gemm g, const Sched& S, const Epi& E, int wv) {
;     ...
;             PG8_LDB(B0, 1, 0); PG8_LDB(B1, 1, 1); PG8_SCHED; PG8_LDA(At, 1, 0); PG8_STAGE(PG8_SA(0, 1), a2 + hstepA, voffA);
;             PG8_WAIT_V(8); PG8_WAIT_L(0); PG8_BAR; PG8_MMA(0, 0, At, B0); PG8_MMA(0, 1, At, B1); PG8_BAR; PG8_SCHED;
;             PG8_LDA(At, 1, 1); PG8_STAGE(PG8_SB(1, 0), b3, voffB); PG8_STAGE(PG8_SB(1, 1), b3 + hstepB, voffB); PG8_STAGE(PG8_SA(1, 0), a3, voffA);
;             PG8_WAIT_V(8); PG8_WAIT_L(0); PG8_BAR; PG8_MMA(1, 0, At, B0); PG8_MMA(1, 1, At, B1); PG8_BAR; PG8_SCHED;
;     ...
;         if constexpr (F8) asm volatile("s_nop 15\n\ts_nop 15" ::: "memory");
	v_add_u32_e32 v12, s61, v181
	v_add_u32_e32 v28, s62, v181
	ds_read_b128 v[0:3], v12
	ds_read_b128 v[4:7], v12 offset:1024
	ds_read_b128 v[8:11], v12 offset:2048
	ds_read_b128 v[12:15], v12 offset:3072
	ds_read_b128 v[16:19], v28
	ds_read_b128 v[20:23], v28 offset:1024
	ds_read_b128 v[24:27], v28 offset:2048
	ds_read_b128 v[28:31], v28 offset:3072
	s_add_u32 s30, s30, 0x40000
	s_addc_u32 s31, s31, 0
	s_mov_b32 m0, s45
	v_lshl_add_u64 v[200:201], s[30:31], 0, v[162:163]
	ds_read_b128 v[184:187], v183 offset:32768
	ds_read_b128 v[188:191], v183 offset:33792
	ds_read_b128 v[192:195], v183 offset:34816
	ds_read_b128 v[196:199], v183 offset:35840
	ds_read_b128 v[214:217], v183 offset:36864
	ds_read_b128 v[218:221], v183 offset:37888
	ds_read_b128 v[222:225], v183 offset:38912
	ds_read_b128 v[226:229], v183 offset:39936
	global_load_lds_dwordx4 v[200:201], off
	v_lshl_add_u64 v[200:201], s[30:31], 0, v[164:165]
	s_mov_b32 m0, s46
	s_nop 0
	global_load_lds_dwordx4 v[200:201], off
	s_waitcnt vmcnt(8)
	s_waitcnt lgkmcnt(0)
	s_barrier
	s_waitcnt lgkmcnt(0)
	v_mfma_f32_16x16x128_f8f6f4 v[158:161], v[0:7], v[184:191], v[158:161]
	v_mfma_f32_16x16x128_f8f6f4 v[154:157], v[8:15], v[184:191], v[154:157]
	v_mfma_f32_16x16x128_f8f6f4 v[146:149], v[0:7], v[192:199], v[146:149]
	v_mfma_f32_16x16x128_f8f6f4 v[138:141], v[8:15], v[192:199], v[138:141]
	v_mfma_f32_16x16x128_f8f6f4 v[130:133], v[0:7], v[214:221], v[130:133]
	v_mfma_f32_16x16x128_f8f6f4 v[120:123], v[8:15], v[214:221], v[120:123]
	v_mfma_f32_16x16x128_f8f6f4 v[112:115], v[0:7], v[222:229], v[112:115]
	v_mfma_f32_16x16x128_f8f6f4 v[104:107], v[8:15], v[222:229], v[104:107]
	v_mfma_f32_16x16x128_f8f6f4 v[150:153], v[16:23], v[184:191], v[150:153]
	v_mfma_f32_16x16x128_f8f6f4 v[142:145], v[24:31], v[184:191], v[142:145]
	v_mfma_f32_16x16x128_f8f6f4 v[134:137], v[16:23], v[192:199], v[134:137]
	v_mfma_f32_16x16x128_f8f6f4 v[124:127], v[24:31], v[192:199], v[124:127]
	v_mfma_f32_16x16x128_f8f6f4 v[116:119], v[16:23], v[214:221], v[116:119]
	v_mfma_f32_16x16x128_f8f6f4 v[108:111], v[24:31], v[214:221], v[108:111]
	v_mfma_f32_16x16x128_f8f6f4 v[100:103], v[16:23], v[222:229], v[100:103]
	v_mfma_f32_16x16x128_f8f6f4 v[96:99], v[24:31], v[222:229], v[96:99]
	s_barrier
	s_mov_b32 m0, s49
	v_lshl_add_u64 v[172:173], v[172:173], 0, s[52:53]
	s_add_u32 s28, s28, 0x40080
	ds_read_b128 v[184:187], v183 offset:49152
	ds_read_b128 v[188:191], v183 offset:50176
	ds_read_b128 v[192:195], v183 offset:51200
	ds_read_b128 v[196:199], v183 offset:52224
	ds_read_b128 v[214:217], v183 offset:53248
	ds_read_b128 v[218:221], v183 offset:54272
	ds_read_b128 v[222:225], v183 offset:55296
	ds_read_b128 v[226:229], v183 offset:56320
	global_load_lds_dwordx4 v[172:173], off
	v_lshl_add_u64 v[172:173], v[174:175], 0, s[52:53]
	s_mov_b32 m0, s54
	s_addc_u32 s29, s29, 0
	global_load_lds_dwordx4 v[172:173], off
	v_lshl_add_u64 v[172:173], s[28:29], 0, v[128:129]
	s_mov_b32 m0, s57
	s_nop 0
	global_load_lds_dwordx4 v[172:173], off
	v_lshl_add_u64 v[172:173], s[28:29], 0, v[166:167]
	s_mov_b32 m0, s58
	s_nop 0
	global_load_lds_dwordx4 v[172:173], off
	v_lshl_add_u64 v[172:173], v[176:177], 0, s[52:53]
	s_mov_b32 m0, s55
	s_nop 0
	global_load_lds_dwordx4 v[172:173], off
	v_lshl_add_u64 v[172:173], v[178:179], 0, s[52:53]
	s_mov_b32 m0, s56
	s_nop 0
	global_load_lds_dwordx4 v[172:173], off
	s_waitcnt vmcnt(8)
	s_waitcnt lgkmcnt(0)
	s_barrier
	s_waitcnt lgkmcnt(0)
	v_mfma_f32_16x16x128_f8f6f4 v[92:95], v[0:7], v[184:191], v[92:95]
	v_mfma_f32_16x16x128_f8f6f4 v[88:91], v[8:15], v[184:191], v[88:91]
	v_mfma_f32_16x16x128_f8f6f4 v[80:83], v[0:7], v[192:199], v[80:83]
	v_mfma_f32_16x16x128_f8f6f4 v[72:75], v[8:15], v[192:199], v[72:75]
	v_mfma_f32_16x16x128_f8f6f4 v[64:67], v[0:7], v[214:221], v[64:67]
	v_mfma_f32_16x16x128_f8f6f4 v[56:59], v[8:15], v[214:221], v[56:59]
	v_mfma_f32_16x16x128_f8f6f4 v[48:51], v[0:7], v[222:229], v[48:51]
	v_mfma_f32_16x16x128_f8f6f4 v[40:43], v[8:15], v[222:229], v[40:43]
	v_mfma_f32_16x16x128_f8f6f4 v[84:87], v[16:23], v[184:191], v[84:87]
	v_mfma_f32_16x16x128_f8f6f4 v[76:79], v[24:31], v[184:191], v[76:79]
	v_mfma_f32_16x16x128_f8f6f4 v[68:71], v[16:23], v[192:199], v[68:71]
	v_mfma_f32_16x16x128_f8f6f4 v[60:63], v[24:31], v[192:199], v[60:63]
	v_mfma_f32_16x16x128_f8f6f4 v[52:55], v[16:23], v[214:221], v[52:55]
	v_mfma_f32_16x16x128_f8f6f4 v[44:47], v[24:31], v[214:221], v[44:47]
	v_mfma_f32_16x16x128_f8f6f4 v[36:39], v[16:23], v[222:229], v[36:39]
	v_mfma_f32_16x16x128_f8f6f4 v[32:35], v[24:31], v[222:229], v[32:35]
	s_barrier
	s_add_i32 s71, s71, 2
	s_add_u32 s26, s26, 0x100
	s_addc_u32 s27, s27, 0
	s_add_u32 s69, s69, 0x100
	s_addc_u32 s70, s70, 0
	s_cmp_gt_u32 s71, 13
	s_cbranch_scc0 .LBB0_286
	s_nop 15
	s_nop 15
	s_and_b64 vcc, exec, s[8:9]
	s_mov_b32 s17, 0x4a04000
	s_cbranch_vccz .LBB0_289
	s_barrier

; __device__ __forceinline__ void xcd_barrier(const XcdBarrier& b) {
;     asm volatile("s_waitcnt vmcnt(0)" ::: "memory");
;     __syncthreads();
;     unsigned xb_z = 0u; asm volatile("" : "+v"(xb_z));
;     if (b.wv == 0 && __builtin_amdgcn_mbcnt_hi(~0u, __builtin_amdgcn_mbcnt_lo(~0u, xb_z)) == 0u) {
;         unsigned* bar = b.bar;
;         __builtin_amdgcn_s_waitcnt(0);
;         unsigned nloc = b.st[0], nx = b.st[1];
;         if (nloc == 0u) { xcd_barrier_complete(bar, b.x, nloc, nx); b.st[0] = nloc; b.st[1] = nx; }
.LBB0_295:
	v_readlane_b32 s0, v254, 30
	s_add_i32 s16, s0, 3
	s_cmp_ge_i32 s16, s83
	s_cbranch_scc1 .LBB0_348
	s_setprio 0
	s_waitcnt vmcnt(0)
	v_readlane_b32 s0, v252, 7
	v_readlane_b32 s1, v252, 8
	v_mov_b32_e32 v0, v129
	s_andn2_b64 vcc, exec, s[0:1]
	s_waitcnt vmcnt(0) lgkmcnt(0)
	s_barrier
	s_cbranch_vccnz .LBB0_347
	v_mbcnt_lo_u32_b32 v0, -1, v0
	v_mbcnt_hi_u32_b32 v0, -1, v0
	v_cmp_eq_u32_e32 vcc, 0, v0
	s_and_saveexec_b64 s[0:1], vcc
	s_cbranch_execz .LBB0_346
	v_mov_b32_e32 v0, s84
	s_waitcnt vmcnt(0) expcnt(0) lgkmcnt(0)
	ds_read_b32 v2, v0
	ds_read_b32 v0, v0 offset:4
	s_waitcnt lgkmcnt(1)
	v_cmp_ne_u32_e32 vcc, 0, v2
	s_cbranch_vccnz .LBB0_314
	s_load_dwordx2 s[2:3], s[90:91], 0x0
	s_load_dword s4, s[90:91], 0x8
	s_mov_b32 s9, 1
	s_waitcnt lgkmcnt(0)
	s_mul_i32 s8, s3, s2
	s_mul_i32 s8, s8, s4
	s_branch .LBB0_301

; __device__ __forceinline__ void xcd_barrier(const XcdBarrier& b) {
;     asm volatile("s_waitcnt vmcnt(0)" ::: "memory");
;     __syncthreads();
;     unsigned xb_z = 0u; asm volatile("" : "+v"(xb_z));
;     if (b.wv == 0 && __builtin_amdgcn_mbcnt_hi(~0u, __builtin_amdgcn_mbcnt_lo(~0u, xb_z)) == 0u) {
;         unsigned* bar = b.bar;
;         __builtin_amdgcn_s_waitcnt(0);
;         unsigned nloc = b.st[0], nx = b.st[1];
;         if (nloc == 0u) { xcd_barrier_complete(bar, b.x, nloc, nx); b.st[0] = nloc; b.st[1] = nx; }
.LBB0_415:
	v_readlane_b32 s0, v254, 30
	s_add_i32 s16, s0, 4
	s_cmp_ge_i32 s16, s83
	s_cbranch_scc1 .LBB0_428
	s_setprio 0
	s_waitcnt vmcnt(0)
	v_readlane_b32 s0, v252, 7
	v_readlane_b32 s1, v252, 8
	s_waitcnt vmcnt(0)
	v_mov_b32_e32 v0, v129
	s_andn2_b64 vcc, exec, s[0:1]
	v_readlane_b32 s15, v254, 35
	s_waitcnt lgkmcnt(0)
	s_barrier
	s_cbranch_vccnz .LBB0_467
	v_mbcnt_lo_u32_b32 v0, -1, v0
	v_mbcnt_hi_u32_b32 v0, -1, v0
	v_cmp_eq_u32_e32 vcc, 0, v0
	s_and_saveexec_b64 s[0:1], vcc
	s_cbranch_execz .LBB0_466
	v_mov_b32_e32 v0, s84
	s_waitcnt vmcnt(0) expcnt(0) lgkmcnt(0)
	ds_read_b32 v2, v0
	ds_read_b32 v0, v0 offset:4
	s_waitcnt lgkmcnt(1)
	v_cmp_ne_u32_e32 vcc, 0, v2
	s_cbranch_vccnz .LBB0_434
	s_load_dwordx2 s[2:3], s[90:91], 0x0
	s_load_dword s4, s[90:91], 0x8
	s_mov_b32 s9, 1
	s_waitcnt lgkmcnt(0)
	s_mul_i32 s8, s3, s2
	s_mul_i32 s8, s8, s4
	s_branch .LBB0_421

; __device__ __forceinline__ void xcd_barrier(const XcdBarrier& b) {
;     asm volatile("s_waitcnt vmcnt(0)" ::: "memory");
;     __syncthreads();
;     unsigned xb_z = 0u; asm volatile("" : "+v"(xb_z));
;     if (b.wv == 0 && __builtin_amdgcn_mbcnt_hi(~0u, __builtin_amdgcn_mbcnt_lo(~0u, xb_z)) == 0u) {
;         unsigned* bar = b.bar;
;         __builtin_amdgcn_s_waitcnt(0);
;         unsigned nloc = b.st[0], nx = b.st[1];
;         if (nloc == 0u) { xcd_barrier_complete(bar, b.x, nloc, nx); b.st[0] = nloc; b.st[1] = nx; }
.LBB0_509:
	v_readlane_b32 s0, v254, 30
	v_readlane_b32 s82, v254, 22
	s_add_i32 s16, s0, 5
	v_readlane_b32 s83, v254, 23
	s_cmp_ge_i32 s16, s83
	s_cbranch_scc1 .LBB0_522
	s_setprio 0
	s_waitcnt vmcnt(0)
	v_readlane_b32 s0, v252, 7
	v_readlane_b32 s1, v252, 8
	v_readlane_b32 s80, v254, 19
	v_readlane_b32 s86, v254, 24
	v_readlane_b32 s90, v254, 28
	v_mov_b32_e32 v0, v129
	s_andn2_b64 vcc, exec, s[0:1]
	v_readlane_b32 s81, v254, 20
	v_readlane_b32 s79, v254, 21
	v_readlane_b32 s87, v254, 25
	v_readlane_b32 s84, v254, 26
	v_readlane_b32 s88, v254, 27
	v_readlane_b32 s91, v254, 29
	s_mov_b32 s17, 0x4a04000
	v_readlane_b32 s92, v254, 36
	v_readlane_b32 s15, v254, 35
	s_barrier
	v_readlane_b32 s93, v254, 37
	s_cbranch_vccnz .LBB0_561
	v_mbcnt_lo_u32_b32 v0, -1, v0
	v_mbcnt_hi_u32_b32 v0, -1, v0
	v_cmp_eq_u32_e32 vcc, 0, v0
	s_and_saveexec_b64 s[0:1], vcc
	s_cbranch_execz .LBB0_560
	v_mov_b32_e32 v0, s84
	s_waitcnt vmcnt(0) expcnt(0) lgkmcnt(0)
	ds_read_b32 v2, v0
	ds_read_b32 v0, v0 offset:4
	s_waitcnt lgkmcnt(1)
	v_cmp_ne_u32_e32 vcc, 0, v2
	s_cbranch_vccnz .LBB0_528
	s_load_dwordx2 s[2:3], s[90:91], 0x0
	s_load_dword s4, s[90:91], 0x8
	s_mov_b32 s9, 1
	s_waitcnt lgkmcnt(0)
	s_mul_i32 s8, s3, s2
	s_mul_i32 s8, s8, s4
	s_branch .LBB0_515

; __device__ __forceinline__ void xcd_barrier(const XcdBarrier& b) {
;     asm volatile("s_waitcnt vmcnt(0)" ::: "memory");
;     __syncthreads();
;     unsigned xb_z = 0u; asm volatile("" : "+v"(xb_z));
;     if (b.wv == 0 && __builtin_amdgcn_mbcnt_hi(~0u, __builtin_amdgcn_mbcnt_lo(~0u, xb_z)) == 0u) {
;         unsigned* bar = b.bar;
;         __builtin_amdgcn_s_waitcnt(0);
;         unsigned nloc = b.st[0], nx = b.st[1];
;         if (nloc == 0u) { xcd_barrier_complete(bar, b.x, nloc, nx); b.st[0] = nloc; b.st[1] = nx; }
.LBB0_574:
	v_readlane_b32 s0, v254, 30
	s_add_i32 s16, s0, 6
	s_cmp_ge_i32 s16, s83
	s_cbranch_scc1 .LBB0_626
	s_setprio 0
	s_waitcnt vmcnt(0)
	v_readlane_b32 s0, v252, 7
	v_readlane_b32 s1, v252, 8
	v_mov_b32_e32 v0, v129
	s_andn2_b64 vcc, exec, s[0:1]
	s_barrier
	s_cbranch_vccnz .LBB0_625
	v_mbcnt_lo_u32_b32 v0, -1, v0
	v_mbcnt_hi_u32_b32 v0, -1, v0
	v_cmp_eq_u32_e32 vcc, 0, v0
	s_and_saveexec_b64 s[0:1], vcc
	s_cbranch_execz .LBB0_624
	v_mov_b32_e32 v0, s84
	s_waitcnt vmcnt(0) expcnt(0) lgkmcnt(0)
	ds_read_b32 v2, v0
	ds_read_b32 v0, v0 offset:4
	s_waitcnt lgkmcnt(1)
	v_cmp_ne_u32_e32 vcc, 0, v2
	s_cbranch_vccnz .LBB0_592
	s_load_dwordx2 s[2:3], s[90:91], 0x0
	s_load_dword s4, s[90:91], 0x8
	s_mov_b32 s9, 1
	s_waitcnt lgkmcnt(0)
	s_mul_i32 s8, s3, s2
	s_mul_i32 s8, s8, s4
	s_branch .LBB0_580

; #define PG8_STAGE(bufoff, gbase, voff) do { _Pragma("unroll") for (int _i = 0; _i < 2; ++_i) \
;         __builtin_amdgcn_global_load_lds((const unsigned*)((const char*)(gbase) + (voff)[_i]), (PG8_LAS unsigned*)(lds + (bufoff) + ldsw + _i * 8192), 16, 0, 0); } while (0)
; #define PG8_LDA(dst, b, h) do { _Pragma("unroll") for (int m = 0; m < 4; ++m) _Pragma("unroll") for (int k = 0; k < 2; ++k) dst[m][k] = *(const PG8_LAS bf16x8*)(lds + PG8_SA(b, h) + aoff + m * 2048 + k * 1024); } while (0)
; #define PG8_LDB(dst, b, h) do { _Pragma("unroll") for (int n = 0; n < 2; ++n) _Pragma("unroll") for (int k = 0; k < 2; ++k) dst[n][k] = *(const PG8_LAS bf16x8*)(lds + (SP2 ? PG8_SB(b, hw) + (h) * 4096 : PG8_SB(b, h)) + boff + n * 2048 + k * 1024); } while (0)
; #define PG8_WAIT_V(n) asm volatile("s_waitcnt vmcnt(" #n ")" ::: "memory")
; #define PG8_WAIT_L(n) asm volatile("s_waitcnt lgkmcnt(" #n ")" ::: "memory")
; #define PG8_BAR __builtin_amdgcn_s_barrier()
; #define PG8_SCHED __builtin_amdgcn_sched_barrier(0)
; template <class Epi, class Sched, bool ALIGN_EPI = false, bool SP2 = false, bool F8 = false>
; __device__ __forceinline__ void gemm_phase(PG8_LAS unsigned char* lds, const Gemm g, const Sched& S, const Epi& E, int wv) {
;     ...
;             const char* a1 = cA + (size_t)(t + 1) * kstep;
;             const char* a2 = last ? nA : cA + (size_t)(t + 2) * kstep; const char* b2 = last ? nB : cB + (size_t)(t + 2) * kstep;
;             const char* a3 = a2 + kstep; const char* b3 = b2 + kstep;
;             if (last && has_next) S.a_ready(nxt);
;             if constexpr (SP2) {
;             PG8_LDB(B0, 0, 0); PG8_LDB(B1, 0, 1); PG8_SCHED; PG8_LDA(At, 0, 0); PG8_STAGE(PG8_SA(1, 1), a1 + hstepA, voffA);
;             PG8_WAIT_V(8); PG8_WAIT_L(0); PG8_BAR; PG8_MMA(0, 0, At, B0); PG8_MMA(0, 1, At, B1); PG8_BAR; PG8_SCHED;
;             PG8_LDA(At, 0, 1); PG8_STAGE(PG8_SB(0, 0), b2, voffB); PG8_STAGE(PG8_SB(0, 1), b2 + hstepB, voffB); PG8_STAGE(PG8_SA(0, 0), a2, voffA);
;             PG8_WAIT_V(8); PG8_WAIT_L(0); PG8_BAR; PG8_MMA(1, 0, At, B0); PG8_MMA(1, 1, At, B1); PG8_BAR; PG8_SCHED;
.LBB0_638:
	v_add_u32_e32 v12, s57, v189
	v_add_u32_e32 v28, s58, v189
	s_add_u32 s22, s18, s20
	ds_read_b128 v[0:3], v12
	ds_read_b128 v[4:7], v12 offset:1024
	ds_read_b128 v[8:11], v12 offset:2048
	ds_read_b128 v[12:15], v12 offset:3072
	ds_read_b128 v[16:19], v28
	ds_read_b128 v[20:23], v28 offset:1024
	ds_read_b128 v[24:27], v28 offset:2048
	ds_read_b128 v[28:31], v28 offset:3072
	s_addc_u32 s23, s19, s21
	s_add_u32 s22, s22, 0x100
	s_addc_u32 s23, s23, 0
	s_add_u32 s67, s71, s20
	s_addc_u32 s74, s72, s21
	s_cmpk_eq_i32 s20, 0x700
	s_cselect_b32 s25, s13, s23
	s_cselect_b32 s24, s63, s22
	s_cselect_b32 s23, s65, s74
	s_cselect_b32 s22, s68, s67
	v_lshl_add_u64 v[130:131], v[176:177], 0, s[20:21]
	s_add_i32 m0, s34, 0xc000
	ds_read_b128 v[192:195], v191
	ds_read_b128 v[196:199], v191 offset:1024
	ds_read_b128 v[214:217], v191 offset:2048
	ds_read_b128 v[218:221], v191 offset:3072
	ds_read_b128 v[222:225], v191 offset:4096
	ds_read_b128 v[226:229], v191 offset:5120
	ds_read_b128 v[230:233], v191 offset:6144
	ds_read_b128 v[234:237], v191 offset:7168
	global_load_lds_dwordx4 v[130:131], off
	v_lshl_add_u64 v[130:131], v[178:179], 0, s[20:21]
	s_add_i32 m0, s34, 0xe000
	s_nop 0
	global_load_lds_dwordx4 v[130:131], off
	s_waitcnt vmcnt(8)
	s_waitcnt lgkmcnt(0)
	s_barrier
	s_cmp_lt_u32 s88, 4
	s_cbranch_scc1 .Lprio_lead_3
	s_setprio 1
.Lprio_lead_3:
	s_waitcnt lgkmcnt(0)
	v_mfma_f32_16x16x128_f8f6f4 v[160:163], v[0:7], v[192:199], v[160:163]
	v_mfma_f32_16x16x128_f8f6f4 v[156:159], v[8:15], v[192:199], v[156:159]
	v_mfma_f32_16x16x128_f8f6f4 v[144:147], v[0:7], v[214:221], v[144:147]
	v_mfma_f32_16x16x128_f8f6f4 v[140:143], v[8:15], v[214:221], v[140:143]
	v_mfma_f32_16x16x128_f8f6f4 v[124:127], v[0:7], v[222:229], v[124:127]
	v_mfma_f32_16x16x128_f8f6f4 v[120:123], v[8:15], v[222:229], v[120:123]
	v_mfma_f32_16x16x128_f8f6f4 v[108:111], v[0:7], v[230:237], v[108:111]
	v_mfma_f32_16x16x128_f8f6f4 v[104:107], v[8:15], v[230:237], v[104:107]
	v_mfma_f32_16x16x128_f8f6f4 v[152:155], v[16:23], v[192:199], v[152:155]
	v_mfma_f32_16x16x128_f8f6f4 v[148:151], v[24:31], v[192:199], v[148:151]
	v_mfma_f32_16x16x128_f8f6f4 v[136:139], v[16:23], v[214:221], v[136:139]
	v_mfma_f32_16x16x128_f8f6f4 v[132:135], v[24:31], v[214:221], v[132:135]
	v_mfma_f32_16x16x128_f8f6f4 v[116:119], v[16:23], v[222:229], v[116:119]
	v_mfma_f32_16x16x128_f8f6f4 v[112:115], v[24:31], v[222:229], v[112:115]
	v_mfma_f32_16x16x128_f8f6f4 v[100:103], v[16:23], v[230:237], v[100:103]
	v_mfma_f32_16x16x128_f8f6f4 v[96:99], v[24:31], v[230:237], v[96:99]
	s_barrier
	s_mov_b32 m0, s35
	v_lshl_add_u64 v[130:131], s[22:23], 0, v[168:169]
	s_add_u32 s74, s22, 0x40000
	ds_read_b128 v[192:195], v191 offset:16384
	ds_read_b128 v[196:199], v191 offset:17408
	ds_read_b128 v[214:217], v191 offset:18432
	ds_read_b128 v[218:221], v191 offset:19456
	ds_read_b128 v[222:225], v191 offset:20480
	ds_read_b128 v[226:229], v191 offset:21504
	ds_read_b128 v[230:233], v191 offset:22528
	ds_read_b128 v[234:237], v191 offset:23552
	global_load_lds_dwordx4 v[130:131], off
	v_lshl_add_u64 v[180:181], s[22:23], 0, v[164:165]
	s_mov_b32 m0, s38
	s_addc_u32 s75, s23, 0
	global_load_lds_dwordx4 v[180:181], off
	v_lshl_add_u64 v[182:183], s[74:75], 0, v[168:169]
	s_mov_b32 m0, s39
	v_lshl_add_u64 v[184:185], s[24:25], 0, v[166:167]
	global_load_lds_dwordx4 v[182:183], off
	v_lshl_add_u64 v[182:183], s[74:75], 0, v[164:165]
	s_mov_b32 m0, s40
	s_nop 0
	global_load_lds_dwordx4 v[182:183], off
	v_lshl_add_u64 v[182:183], s[24:25], 0, v[170:171]
	s_mov_b32 m0, s34
	s_nop 0
	global_load_lds_dwordx4 v[182:183], off
	s_mov_b32 m0, s41
	s_nop 0
	global_load_lds_dwordx4 v[184:185], off
	s_waitcnt vmcnt(8)
	s_waitcnt lgkmcnt(0)
	s_barrier
	s_waitcnt lgkmcnt(0)
	v_mfma_f32_16x16x128_f8f6f4 v[92:95], v[0:7], v[192:199], v[92:95]
	v_mfma_f32_16x16x128_f8f6f4 v[88:91], v[8:15], v[192:199], v[88:91]
	v_mfma_f32_16x16x128_f8f6f4 v[76:79], v[0:7], v[214:221], v[76:79]
	v_mfma_f32_16x16x128_f8f6f4 v[72:75], v[8:15], v[214:221], v[72:75]
	v_mfma_f32_16x16x128_f8f6f4 v[60:63], v[0:7], v[222:229], v[60:63]
	v_mfma_f32_16x16x128_f8f6f4 v[56:59], v[8:15], v[222:229], v[56:59]
	v_mfma_f32_16x16x128_f8f6f4 v[44:47], v[0:7], v[230:237], v[44:47]
	v_mfma_f32_16x16x128_f8f6f4 v[40:43], v[8:15], v[230:237], v[40:43]
	v_mfma_f32_16x16x128_f8f6f4 v[84:87], v[16:23], v[192:199], v[84:87]
	v_mfma_f32_16x16x128_f8f6f4 v[80:83], v[24:31], v[192:199], v[80:83]
	v_mfma_f32_16x16x128_f8f6f4 v[68:71], v[16:23], v[214:221], v[68:71]
	v_mfma_f32_16x16x128_f8f6f4 v[64:67], v[24:31], v[214:221], v[64:67]
	v_mfma_f32_16x16x128_f8f6f4 v[52:55], v[16:23], v[222:229], v[52:55]
	v_mfma_f32_16x16x128_f8f6f4 v[48:51], v[24:31], v[222:229], v[48:51]
	v_mfma_f32_16x16x128_f8f6f4 v[36:39], v[16:23], v[230:237], v[36:39]
	v_mfma_f32_16x16x128_f8f6f4 v[32:35], v[24:31], v[230:237], v[32:35]
	s_barrier
; #define PG8_STAGE(bufoff, gbase, voff) do { _Pragma("unroll") for (int _i = 0; _i < 2; ++_i) \
;         __builtin_amdgcn_global_load_lds((const unsigned*)((const char*)(gbase) + (voff)[_i]), (PG8_LAS unsigned*)(lds + (bufoff) + ldsw + _i * 8192), 16, 0, 0); } while (0)
; #define PG8_LDA(dst, b, h) do { _Pragma("unroll") for (int m = 0; m < 4; ++m) _Pragma("unroll") for (int k = 0; k < 2; ++k) dst[m][k] = *(const PG8_LAS bf16x8*)(lds + PG8_SA(b, h) + aoff + m * 2048 + k * 1024); } while (0)
; #define PG8_LDB(dst, b, h) do { _Pragma("unroll") for (int n = 0; n < 2; ++n) _Pragma("unroll") for (int k = 0; k < 2; ++k) dst[n][k] = *(const PG8_LAS bf16x8*)(lds + (SP2 ? PG8_SB(b, hw) + (h) * 4096 : PG8_SB(b, h)) + boff + n * 2048 + k * 1024); } while (0)
; #define PG8_WAIT_V(n) asm volatile("s_waitcnt vmcnt(" #n ")" ::: "memory")
; #define PG8_WAIT_L(n) asm volatile("s_waitcnt lgkmcnt(" #n ")" ::: "memory")
; #define PG8_BAR __builtin_amdgcn_s_barrier()
; #define PG8_SCHED __builtin_amdgcn_sched_barrier(0)
; template <class Epi, class Sched, bool ALIGN_EPI = false, bool SP2 = false, bool F8 = false>
; __device__ __forceinline__ void gemm_phase(PG8_LAS unsigned char* lds, const Gemm g, const Sched& S, const Epi& E, int wv) {
;     ...
;             PG8_LDB(B0, 1, 0); PG8_LDB(B1, 1, 1); PG8_SCHED; PG8_LDA(At, 1, 0); PG8_STAGE(PG8_SA(0, 1), a2 + hstepA, voffA);
;             PG8_WAIT_V(8); PG8_WAIT_L(0); PG8_BAR; PG8_MMA(0, 0, At, B0); PG8_MMA(0, 1, At, B1); PG8_BAR; PG8_SCHED;
;             PG8_LDA(At, 1, 1); PG8_STAGE(PG8_SB(1, 0), b3, voffB); PG8_STAGE(PG8_SB(1, 1), b3 + hstepB, voffB); PG8_STAGE(PG8_SA(1, 0), a3, voffA);
;             PG8_WAIT_V(8); PG8_WAIT_L(0); PG8_BAR; PG8_MMA(1, 0, At, B0); PG8_MMA(1, 1, At, B1); PG8_BAR; PG8_SCHED;
	v_add_u32_e32 v0, s59, v189
	v_add_u32_e32 v4, s60, v189
	ds_read_b128 v[24:27], v0
	ds_read_b128 v[28:31], v0 offset:1024
	ds_read_b128 v[16:19], v0 offset:2048
	ds_read_b128 v[20:23], v0 offset:3072
	ds_read_b128 v[8:11], v4
	ds_read_b128 v[12:15], v4 offset:1024
	ds_read_b128 v[0:3], v4 offset:2048
	ds_read_b128 v[4:7], v4 offset:3072
	s_add_u32 s24, s24, 0x40000
	s_addc_u32 s25, s25, 0
	s_mov_b32 m0, s42
	v_lshl_add_u64 v[200:201], s[24:25], 0, v[170:171]
	ds_read_b128 v[192:195], v191 offset:32768
	ds_read_b128 v[196:199], v191 offset:33792
	ds_read_b128 v[214:217], v191 offset:34816
	ds_read_b128 v[218:221], v191 offset:35840
	ds_read_b128 v[222:225], v191 offset:36864
	ds_read_b128 v[226:229], v191 offset:37888
	ds_read_b128 v[230:233], v191 offset:38912
	ds_read_b128 v[234:237], v191 offset:39936
	global_load_lds_dwordx4 v[200:201], off
	v_lshl_add_u64 v[200:201], s[24:25], 0, v[166:167]
	s_mov_b32 m0, s43
	s_nop 0
	global_load_lds_dwordx4 v[200:201], off
	s_waitcnt vmcnt(8)
	s_waitcnt lgkmcnt(0)
	s_barrier
	s_waitcnt lgkmcnt(0)
	v_mfma_f32_16x16x128_f8f6f4 v[160:163], v[24:31], v[192:199], v[160:163]
	v_mfma_f32_16x16x128_f8f6f4 v[156:159], v[16:23], v[192:199], v[156:159]
	v_mfma_f32_16x16x128_f8f6f4 v[144:147], v[24:31], v[214:221], v[144:147]
	v_mfma_f32_16x16x128_f8f6f4 v[140:143], v[16:23], v[214:221], v[140:143]
	v_mfma_f32_16x16x128_f8f6f4 v[124:127], v[24:31], v[222:229], v[124:127]
	v_mfma_f32_16x16x128_f8f6f4 v[120:123], v[16:23], v[222:229], v[120:123]
	v_mfma_f32_16x16x128_f8f6f4 v[108:111], v[24:31], v[230:237], v[108:111]
	v_mfma_f32_16x16x128_f8f6f4 v[104:107], v[16:23], v[230:237], v[104:107]
	v_mfma_f32_16x16x128_f8f6f4 v[152:155], v[8:15], v[192:199], v[152:155]
	v_mfma_f32_16x16x128_f8f6f4 v[148:151], v[0:7], v[192:199], v[148:151]
	v_mfma_f32_16x16x128_f8f6f4 v[136:139], v[8:15], v[214:221], v[136:139]
	v_mfma_f32_16x16x128_f8f6f4 v[132:135], v[0:7], v[214:221], v[132:135]
	v_mfma_f32_16x16x128_f8f6f4 v[116:119], v[8:15], v[222:229], v[116:119]
	v_mfma_f32_16x16x128_f8f6f4 v[112:115], v[0:7], v[222:229], v[112:115]
	v_mfma_f32_16x16x128_f8f6f4 v[100:103], v[8:15], v[230:237], v[100:103]
	v_mfma_f32_16x16x128_f8f6f4 v[96:99], v[0:7], v[230:237], v[96:99]
	s_barrier
	s_mov_b32 m0, s46
	v_lshl_add_u64 v[130:131], v[130:131], 0, s[52:53]
	s_add_u32 s22, s22, 0x40080
	ds_read_b128 v[192:195], v191 offset:49152
	ds_read_b128 v[196:199], v191 offset:50176
	ds_read_b128 v[214:217], v191 offset:51200
	ds_read_b128 v[218:221], v191 offset:52224
	ds_read_b128 v[222:225], v191 offset:53248
	ds_read_b128 v[226:229], v191 offset:54272
	ds_read_b128 v[230:233], v191 offset:55296
	ds_read_b128 v[234:237], v191 offset:56320
	global_load_lds_dwordx4 v[130:131], off
	v_lshl_add_u64 v[130:131], v[180:181], 0, s[52:53]
	s_mov_b32 m0, s47
	s_addc_u32 s23, s23, 0
	global_load_lds_dwordx4 v[130:131], off
	v_lshl_add_u64 v[130:131], s[22:23], 0, v[168:169]
	s_mov_b32 m0, s54
	s_nop 0
	global_load_lds_dwordx4 v[130:131], off
	v_lshl_add_u64 v[130:131], s[22:23], 0, v[164:165]
	s_mov_b32 m0, s55
	s_nop 0
	global_load_lds_dwordx4 v[130:131], off
	v_lshl_add_u64 v[130:131], v[182:183], 0, s[52:53]
	s_mov_b32 m0, s48
	s_nop 0
	global_load_lds_dwordx4 v[130:131], off
	v_lshl_add_u64 v[130:131], v[184:185], 0, s[52:53]
	s_mov_b32 m0, s49
	s_nop 0
	global_load_lds_dwordx4 v[130:131], off
	s_waitcnt vmcnt(8)
	s_waitcnt lgkmcnt(0)
	s_barrier
	s_waitcnt lgkmcnt(0)
	v_mfma_f32_16x16x128_f8f6f4 v[92:95], v[24:31], v[192:199], v[92:95]
	v_mfma_f32_16x16x128_f8f6f4 v[88:91], v[16:23], v[192:199], v[88:91]
	v_mfma_f32_16x16x128_f8f6f4 v[76:79], v[24:31], v[214:221], v[76:79]
	v_mfma_f32_16x16x128_f8f6f4 v[72:75], v[16:23], v[214:221], v[72:75]
	v_mfma_f32_16x16x128_f8f6f4 v[60:63], v[24:31], v[222:229], v[60:63]
	v_mfma_f32_16x16x128_f8f6f4 v[56:59], v[16:23], v[222:229], v[56:59]
	v_mfma_f32_16x16x128_f8f6f4 v[44:47], v[24:31], v[230:237], v[44:47]
	v_mfma_f32_16x16x128_f8f6f4 v[40:43], v[16:23], v[230:237], v[40:43]
	v_mfma_f32_16x16x128_f8f6f4 v[84:87], v[8:15], v[192:199], v[84:87]
	v_mfma_f32_16x16x128_f8f6f4 v[80:83], v[0:7], v[192:199], v[80:83]
	v_mfma_f32_16x16x128_f8f6f4 v[68:71], v[8:15], v[214:221], v[68:71]
	v_mfma_f32_16x16x128_f8f6f4 v[64:67], v[0:7], v[214:221], v[64:67]
	v_mfma_f32_16x16x128_f8f6f4 v[52:55], v[8:15], v[222:229], v[52:55]
	v_mfma_f32_16x16x128_f8f6f4 v[48:51], v[0:7], v[222:229], v[48:51]
	v_mfma_f32_16x16x128_f8f6f4 v[36:39], v[8:15], v[230:237], v[36:39]
	v_mfma_f32_16x16x128_f8f6f4 v[32:35], v[0:7], v[230:237], v[32:35]
	s_barrier
	s_add_i32 s73, s73, 2
	s_add_u32 s20, s20, 0x100
	s_addc_u32 s21, s21, 0
	s_cmp_gt_u32 s73, 13
	s_cbranch_scc1 .LBB0_641

; __device__ __forceinline__ void xcd_barrier(const XcdBarrier& b) {
;     asm volatile("s_waitcnt vmcnt(0)" ::: "memory");
;     __syncthreads();
;     unsigned xb_z = 0u; asm volatile("" : "+v"(xb_z));
;     if (b.wv == 0 && __builtin_amdgcn_mbcnt_hi(~0u, __builtin_amdgcn_mbcnt_lo(~0u, xb_z)) == 0u) {
;         unsigned* bar = b.bar;
;         __builtin_amdgcn_s_waitcnt(0);
;         unsigned nloc = b.st[0], nx = b.st[1];
;         if (nloc == 0u) { xcd_barrier_complete(bar, b.x, nloc, nx); b.st[0] = nloc; b.st[1] = nx; }
.LBB0_647:
	v_readlane_b32 s0, v254, 30
	s_add_i32 s16, s0, 7
	s_cmp_ge_i32 s16, s83
	s_cbranch_scc1 .LBB0_699
	s_setprio 0
	s_waitcnt vmcnt(0)
	v_readlane_b32 s0, v252, 7
	v_readlane_b32 s1, v252, 8
	v_mov_b32_e32 v0, v129
	s_andn2_b64 vcc, exec, s[0:1]
	s_waitcnt lgkmcnt(0)
	s_barrier
	s_cbranch_vccnz .LBB0_698
	v_mbcnt_lo_u32_b32 v0, -1, v0
	v_mbcnt_hi_u32_b32 v0, -1, v0
	v_cmp_eq_u32_e32 vcc, 0, v0
	s_and_saveexec_b64 s[0:1], vcc
	s_cbranch_execz .LBB0_697
	v_mov_b32_e32 v0, s84
	s_waitcnt vmcnt(0) expcnt(0) lgkmcnt(0)
	ds_read_b32 v2, v0
	ds_read_b32 v0, v0 offset:4
	s_waitcnt lgkmcnt(1)
	v_cmp_ne_u32_e32 vcc, 0, v2
	s_cbranch_vccnz .LBB0_665
	s_load_dwordx2 s[2:3], s[90:91], 0x0
	s_load_dword s4, s[90:91], 0x8
	s_mov_b32 s9, 1
	s_waitcnt lgkmcnt(0)
	s_mul_i32 s8, s3, s2
	s_mul_i32 s8, s8, s4
	s_branch .LBB0_653

; #define PG8_STAGE(bufoff, gbase, voff) do { _Pragma("unroll") for (int _i = 0; _i < 2; ++_i) \
;         __builtin_amdgcn_global_load_lds((const unsigned*)((const char*)(gbase) + (voff)[_i]), (PG8_LAS unsigned*)(lds + (bufoff) + ldsw + _i * 8192), 16, 0, 0); } while (0)
; #define PG8_LDA(dst, b, h) do { _Pragma("unroll") for (int m = 0; m < 4; ++m) _Pragma("unroll") for (int k = 0; k < 2; ++k) dst[m][k] = *(const PG8_LAS bf16x8*)(lds + PG8_SA(b, h) + aoff + m * 2048 + k * 1024); } while (0)
; #define PG8_LDB(dst, b, h) do { _Pragma("unroll") for (int n = 0; n < 2; ++n) _Pragma("unroll") for (int k = 0; k < 2; ++k) dst[n][k] = *(const PG8_LAS bf16x8*)(lds + (SP2 ? PG8_SB(b, hw) + (h) * 4096 : PG8_SB(b, h)) + boff + n * 2048 + k * 1024); } while (0)
; #define PG8_WAIT_V(n) asm volatile("s_waitcnt vmcnt(" #n ")" ::: "memory")
; #define PG8_WAIT_L(n) asm volatile("s_waitcnt lgkmcnt(" #n ")" ::: "memory")
; #define PG8_BAR __builtin_amdgcn_s_barrier()
; #define PG8_SCHED __builtin_amdgcn_sched_barrier(0)
; template <class Epi, class Sched, bool ALIGN_EPI = false, bool SP2 = false, bool F8 = false>
; __device__ __forceinline__ void gemm_phase(PG8_LAS unsigned char* lds, const Gemm g, const Sched& S, const Epi& E, int wv) {
;     ...
;             const char* a1 = cA + (size_t)(t + 1) * kstep;
;             const char* a2 = last ? nA : cA + (size_t)(t + 2) * kstep; const char* b2 = last ? nB : cB + (size_t)(t + 2) * kstep;
;             const char* a3 = a2 + kstep; const char* b3 = b2 + kstep;
;             if (last && has_next) S.a_ready(nxt);
;             if constexpr (SP2) {
;             PG8_LDB(B0, 0, 0); PG8_LDB(B1, 0, 1); PG8_SCHED; PG8_LDA(At, 0, 0); PG8_STAGE(PG8_SA(1, 1), a1 + hstepA, voffA);
;             PG8_WAIT_V(8); PG8_WAIT_L(0); PG8_BAR; PG8_MMA(0, 0, At, B0); PG8_MMA(0, 1, At, B1); PG8_BAR; PG8_SCHED;
;             PG8_LDA(At, 0, 1); PG8_STAGE(PG8_SB(0, 0), b2, voffB); PG8_STAGE(PG8_SB(0, 1), b2 + hstepB, voffB); PG8_STAGE(PG8_SA(0, 0), a2, voffA);
;             PG8_WAIT_V(8); PG8_WAIT_L(0); PG8_BAR; PG8_MMA(1, 0, At, B0); PG8_MMA(1, 1, At, B1); PG8_BAR; PG8_SCHED;
.LBB0_711:
	v_add_u32_e32 v0, s48, v181
	v_add_u32_e32 v4, s49, v181
	ds_read_b128 v[24:27], v0
	ds_read_b128 v[28:31], v0 offset:1024
	ds_read_b128 v[16:19], v0 offset:2048
	ds_read_b128 v[20:23], v0 offset:3072
	ds_read_b128 v[8:11], v4
	ds_read_b128 v[12:15], v4 offset:1024
	ds_read_b128 v[0:3], v4 offset:2048
	ds_read_b128 v[4:7], v4 offset:3072
	s_add_u32 s20, s18, 0xfffc0080
	s_addc_u32 s21, s19, -1
	s_cmp_eq_u32 s61, 12
	s_cselect_b32 s23, s9, s21
	s_cselect_b32 s22, s15, s20
	s_cselect_b32 s21, s7, s60
	s_cselect_b32 s20, s58, s59
	v_lshl_add_u64 v[200:201], s[18:19], 0, v[168:169]
	s_add_i32 m0, s17, 0xc000
	ds_read_b128 v[172:175], v183
	ds_read_b128 v[176:179], v183 offset:1024
	ds_read_b128 v[184:187], v183 offset:2048
	ds_read_b128 v[188:191], v183 offset:3072
	ds_read_b128 v[192:195], v183 offset:4096
	ds_read_b128 v[196:199], v183 offset:5120
	ds_read_b128 v[214:217], v183 offset:6144
	ds_read_b128 v[218:221], v183 offset:7168
	global_load_lds_dwordx4 v[200:201], off
	v_lshl_add_u64 v[200:201], s[18:19], 0, v[170:171]
	s_add_i32 m0, s17, 0xe000
	s_nop 0
	global_load_lds_dwordx4 v[200:201], off
	s_waitcnt vmcnt(8)
	s_waitcnt lgkmcnt(0)
	s_barrier
	s_cmp_lt_u32 s88, 4
	s_cbranch_scc1 .Lprio_lead_4
	s_setprio 1
.Lprio_lead_4:
	s_waitcnt lgkmcnt(0)
	v_mfma_f32_16x16x128_f8f6f4 v[158:161], v[24:31], v[172:179], v[158:161]
	v_mfma_f32_16x16x128_f8f6f4 v[154:157], v[16:23], v[172:179], v[154:157]
	v_mfma_f32_16x16x128_f8f6f4 v[146:149], v[24:31], v[184:191], v[146:149]
	v_mfma_f32_16x16x128_f8f6f4 v[138:141], v[16:23], v[184:191], v[138:141]
	v_mfma_f32_16x16x128_f8f6f4 v[130:133], v[24:31], v[192:199], v[130:133]
	v_mfma_f32_16x16x128_f8f6f4 v[120:123], v[16:23], v[192:199], v[120:123]
	v_mfma_f32_16x16x128_f8f6f4 v[112:115], v[24:31], v[214:221], v[112:115]
	v_mfma_f32_16x16x128_f8f6f4 v[104:107], v[16:23], v[214:221], v[104:107]
	v_mfma_f32_16x16x128_f8f6f4 v[150:153], v[8:15], v[172:179], v[150:153]
	v_mfma_f32_16x16x128_f8f6f4 v[142:145], v[0:7], v[172:179], v[142:145]
	v_mfma_f32_16x16x128_f8f6f4 v[134:137], v[8:15], v[184:191], v[134:137]
	v_mfma_f32_16x16x128_f8f6f4 v[124:127], v[0:7], v[184:191], v[124:127]
	v_mfma_f32_16x16x128_f8f6f4 v[116:119], v[8:15], v[192:199], v[116:119]
	v_mfma_f32_16x16x128_f8f6f4 v[108:111], v[0:7], v[192:199], v[108:111]
	v_mfma_f32_16x16x128_f8f6f4 v[100:103], v[8:15], v[214:221], v[100:103]
	v_mfma_f32_16x16x128_f8f6f4 v[96:99], v[0:7], v[214:221], v[96:99]
	s_barrier
	s_mov_b32 m0, s30
	v_lshl_add_u64 v[172:173], s[20:21], 0, v[128:129]
	s_add_u32 s62, s20, 0x40000
	ds_read_b128 v[184:187], v183 offset:16384
	ds_read_b128 v[188:191], v183 offset:17408
	ds_read_b128 v[192:195], v183 offset:18432
	ds_read_b128 v[196:199], v183 offset:19456
	ds_read_b128 v[214:217], v183 offset:20480
	ds_read_b128 v[218:221], v183 offset:21504
	ds_read_b128 v[222:225], v183 offset:22528
	ds_read_b128 v[226:229], v183 offset:23552
	global_load_lds_dwordx4 v[172:173], off
	v_lshl_add_u64 v[174:175], s[20:21], 0, v[162:163]
	s_mov_b32 m0, s31
	s_addc_u32 s63, s21, 0
	global_load_lds_dwordx4 v[174:175], off
	v_lshl_add_u64 v[176:177], s[62:63], 0, v[128:129]
	s_mov_b32 m0, s34
	v_lshl_add_u64 v[178:179], s[22:23], 0, v[164:165]
	global_load_lds_dwordx4 v[176:177], off
	v_lshl_add_u64 v[176:177], s[62:63], 0, v[162:163]
	s_mov_b32 m0, s35
	s_nop 0
	global_load_lds_dwordx4 v[176:177], off
	v_lshl_add_u64 v[176:177], s[22:23], 0, v[166:167]
	s_mov_b32 m0, s17
	s_nop 0
	global_load_lds_dwordx4 v[176:177], off
	s_mov_b32 m0, s38
	s_nop 0
	global_load_lds_dwordx4 v[178:179], off
	s_waitcnt vmcnt(8)
	s_waitcnt lgkmcnt(0)
	s_barrier
	s_waitcnt lgkmcnt(0)
	v_mfma_f32_16x16x128_f8f6f4 v[92:95], v[24:31], v[184:191], v[92:95]
	v_mfma_f32_16x16x128_f8f6f4 v[88:91], v[16:23], v[184:191], v[88:91]
	v_mfma_f32_16x16x128_f8f6f4 v[80:83], v[24:31], v[192:199], v[80:83]
	v_mfma_f32_16x16x128_f8f6f4 v[72:75], v[16:23], v[192:199], v[72:75]
	v_mfma_f32_16x16x128_f8f6f4 v[64:67], v[24:31], v[214:221], v[64:67]
	v_mfma_f32_16x16x128_f8f6f4 v[56:59], v[16:23], v[214:221], v[56:59]
	v_mfma_f32_16x16x128_f8f6f4 v[48:51], v[24:31], v[222:229], v[48:51]
	v_mfma_f32_16x16x128_f8f6f4 v[40:43], v[16:23], v[222:229], v[40:43]
	v_mfma_f32_16x16x128_f8f6f4 v[84:87], v[8:15], v[184:191], v[84:87]
	v_mfma_f32_16x16x128_f8f6f4 v[76:79], v[0:7], v[184:191], v[76:79]
	v_mfma_f32_16x16x128_f8f6f4 v[68:71], v[8:15], v[192:199], v[68:71]
	v_mfma_f32_16x16x128_f8f6f4 v[60:63], v[0:7], v[192:199], v[60:63]
	v_mfma_f32_16x16x128_f8f6f4 v[52:55], v[8:15], v[214:221], v[52:55]
	v_mfma_f32_16x16x128_f8f6f4 v[44:47], v[0:7], v[214:221], v[44:47]
	v_mfma_f32_16x16x128_f8f6f4 v[36:39], v[8:15], v[222:229], v[36:39]
	v_mfma_f32_16x16x128_f8f6f4 v[32:35], v[0:7], v[222:229], v[32:35]
	s_barrier
; #define PG8_STAGE(bufoff, gbase, voff) do { _Pragma("unroll") for (int _i = 0; _i < 2; ++_i) \
;         __builtin_amdgcn_global_load_lds((const unsigned*)((const char*)(gbase) + (voff)[_i]), (PG8_LAS unsigned*)(lds + (bufoff) + ldsw + _i * 8192), 16, 0, 0); } while (0)
; #define PG8_LDA(dst, b, h) do { _Pragma("unroll") for (int m = 0; m < 4; ++m) _Pragma("unroll") for (int k = 0; k < 2; ++k) dst[m][k] = *(const PG8_LAS bf16x8*)(lds + PG8_SA(b, h) + aoff + m * 2048 + k * 1024); } while (0)
; #define PG8_LDB(dst, b, h) do { _Pragma("unroll") for (int n = 0; n < 2; ++n) _Pragma("unroll") for (int k = 0; k < 2; ++k) dst[n][k] = *(const PG8_LAS bf16x8*)(lds + (SP2 ? PG8_SB(b, hw) + (h) * 4096 : PG8_SB(b, h)) + boff + n * 2048 + k * 1024); } while (0)
; #define PG8_WAIT_V(n) asm volatile("s_waitcnt vmcnt(" #n ")" ::: "memory")
; #define PG8_WAIT_L(n) asm volatile("s_waitcnt lgkmcnt(" #n ")" ::: "memory")
; #define PG8_BAR __builtin_amdgcn_s_barrier()
; #define PG8_SCHED __builtin_amdgcn_sched_barrier(0)
; template <class Epi, class Sched, bool ALIGN_EPI = false, bool SP2 = false, bool F8 = false>
; __device__ __forceinline__ void gemm_phase(PG8_LAS unsigned char* lds, const Gemm g, const Sched& S, const Epi& E, int wv) {
;     ...
;             PG8_LDB(B0, 1, 0); PG8_LDB(B1, 1, 1); PG8_SCHED; PG8_LDA(At, 1, 0); PG8_STAGE(PG8_SA(0, 1), a2 + hstepA, voffA);
;             PG8_WAIT_V(8); PG8_WAIT_L(0); PG8_BAR; PG8_MMA(0, 0, At, B0); PG8_MMA(0, 1, At, B1); PG8_BAR; PG8_SCHED;
;             PG8_LDA(At, 1, 1); PG8_STAGE(PG8_SB(1, 0), b3, voffB); PG8_STAGE(PG8_SB(1, 1), b3 + hstepB, voffB); PG8_STAGE(PG8_SA(1, 0), a3, voffA);
;             PG8_WAIT_V(8); PG8_WAIT_L(0); PG8_BAR; PG8_MMA(1, 0, At, B0); PG8_MMA(1, 1, At, B1); PG8_BAR; PG8_SCHED;
;     ...
;         if constexpr (F8) asm volatile("s_nop 15\n\ts_nop 15" ::: "memory");
	v_add_u32_e32 v12, s54, v181
	v_add_u32_e32 v28, s55, v181
	ds_read_b128 v[0:3], v12
	ds_read_b128 v[4:7], v12 offset:1024
	ds_read_b128 v[8:11], v12 offset:2048
	ds_read_b128 v[12:15], v12 offset:3072
	ds_read_b128 v[16:19], v28
	ds_read_b128 v[20:23], v28 offset:1024
	ds_read_b128 v[24:27], v28 offset:2048
	ds_read_b128 v[28:31], v28 offset:3072
	s_add_u32 s22, s22, 0x40000
	s_addc_u32 s23, s23, 0
	s_mov_b32 m0, s39
	v_lshl_add_u64 v[200:201], s[22:23], 0, v[166:167]
	ds_read_b128 v[184:187], v183 offset:32768
	ds_read_b128 v[188:191], v183 offset:33792
	ds_read_b128 v[192:195], v183 offset:34816
	ds_read_b128 v[196:199], v183 offset:35840
	ds_read_b128 v[214:217], v183 offset:36864
	ds_read_b128 v[218:221], v183 offset:37888
	ds_read_b128 v[222:225], v183 offset:38912
	ds_read_b128 v[226:229], v183 offset:39936
	global_load_lds_dwordx4 v[200:201], off
	v_lshl_add_u64 v[200:201], s[22:23], 0, v[164:165]
	s_mov_b32 m0, s40
	s_nop 0
	global_load_lds_dwordx4 v[200:201], off
	s_waitcnt vmcnt(8)
	s_waitcnt lgkmcnt(0)
	s_barrier
	s_waitcnt lgkmcnt(0)
	v_mfma_f32_16x16x128_f8f6f4 v[158:161], v[0:7], v[184:191], v[158:161]
	v_mfma_f32_16x16x128_f8f6f4 v[154:157], v[8:15], v[184:191], v[154:157]
	v_mfma_f32_16x16x128_f8f6f4 v[146:149], v[0:7], v[192:199], v[146:149]
	v_mfma_f32_16x16x128_f8f6f4 v[138:141], v[8:15], v[192:199], v[138:141]
	v_mfma_f32_16x16x128_f8f6f4 v[130:133], v[0:7], v[214:221], v[130:133]
	v_mfma_f32_16x16x128_f8f6f4 v[120:123], v[8:15], v[214:221], v[120:123]
	v_mfma_f32_16x16x128_f8f6f4 v[112:115], v[0:7], v[222:229], v[112:115]
	v_mfma_f32_16x16x128_f8f6f4 v[104:107], v[8:15], v[222:229], v[104:107]
	v_mfma_f32_16x16x128_f8f6f4 v[150:153], v[16:23], v[184:191], v[150:153]
	v_mfma_f32_16x16x128_f8f6f4 v[142:145], v[24:31], v[184:191], v[142:145]
	v_mfma_f32_16x16x128_f8f6f4 v[134:137], v[16:23], v[192:199], v[134:137]
	v_mfma_f32_16x16x128_f8f6f4 v[124:127], v[24:31], v[192:199], v[124:127]
	v_mfma_f32_16x16x128_f8f6f4 v[116:119], v[16:23], v[214:221], v[116:119]
	v_mfma_f32_16x16x128_f8f6f4 v[108:111], v[24:31], v[214:221], v[108:111]
	v_mfma_f32_16x16x128_f8f6f4 v[100:103], v[16:23], v[222:229], v[100:103]
	v_mfma_f32_16x16x128_f8f6f4 v[96:99], v[24:31], v[222:229], v[96:99]
	s_barrier
	s_mov_b32 m0, s42
	v_lshl_add_u64 v[172:173], v[172:173], 0, s[52:53]
	s_add_u32 s20, s20, 0x40080
	ds_read_b128 v[184:187], v183 offset:49152
	ds_read_b128 v[188:191], v183 offset:50176
	ds_read_b128 v[192:195], v183 offset:51200
	ds_read_b128 v[196:199], v183 offset:52224
	ds_read_b128 v[214:217], v183 offset:53248
	ds_read_b128 v[218:221], v183 offset:54272
	ds_read_b128 v[222:225], v183 offset:55296
	ds_read_b128 v[226:229], v183 offset:56320
	global_load_lds_dwordx4 v[172:173], off
	v_lshl_add_u64 v[172:173], v[174:175], 0, s[52:53]
	s_mov_b32 m0, s43
	s_addc_u32 s21, s21, 0
	global_load_lds_dwordx4 v[172:173], off
	v_lshl_add_u64 v[172:173], s[20:21], 0, v[128:129]
	s_mov_b32 m0, s46
	s_nop 0
	global_load_lds_dwordx4 v[172:173], off
	v_lshl_add_u64 v[172:173], s[20:21], 0, v[162:163]
	s_mov_b32 m0, s47
	s_nop 0
	global_load_lds_dwordx4 v[172:173], off
	v_lshl_add_u64 v[172:173], v[176:177], 0, s[52:53]
	s_mov_b32 m0, s44
	s_nop 0
	global_load_lds_dwordx4 v[172:173], off
	v_lshl_add_u64 v[172:173], v[178:179], 0, s[52:53]
	s_mov_b32 m0, s45
	s_nop 0
	global_load_lds_dwordx4 v[172:173], off
	s_waitcnt vmcnt(8)
	s_waitcnt lgkmcnt(0)
	s_barrier
	s_waitcnt lgkmcnt(0)
	v_mfma_f32_16x16x128_f8f6f4 v[92:95], v[0:7], v[184:191], v[92:95]
	v_mfma_f32_16x16x128_f8f6f4 v[88:91], v[8:15], v[184:191], v[88:91]
	v_mfma_f32_16x16x128_f8f6f4 v[80:83], v[0:7], v[192:199], v[80:83]
	v_mfma_f32_16x16x128_f8f6f4 v[72:75], v[8:15], v[192:199], v[72:75]
	v_mfma_f32_16x16x128_f8f6f4 v[64:67], v[0:7], v[214:221], v[64:67]
	v_mfma_f32_16x16x128_f8f6f4 v[56:59], v[8:15], v[214:221], v[56:59]
	v_mfma_f32_16x16x128_f8f6f4 v[48:51], v[0:7], v[222:229], v[48:51]
	v_mfma_f32_16x16x128_f8f6f4 v[40:43], v[8:15], v[222:229], v[40:43]
	v_mfma_f32_16x16x128_f8f6f4 v[84:87], v[16:23], v[184:191], v[84:87]
	v_mfma_f32_16x16x128_f8f6f4 v[76:79], v[24:31], v[184:191], v[76:79]
	v_mfma_f32_16x16x128_f8f6f4 v[68:71], v[16:23], v[192:199], v[68:71]
	v_mfma_f32_16x16x128_f8f6f4 v[60:63], v[24:31], v[192:199], v[60:63]
	v_mfma_f32_16x16x128_f8f6f4 v[52:55], v[16:23], v[214:221], v[52:55]
	v_mfma_f32_16x16x128_f8f6f4 v[44:47], v[24:31], v[214:221], v[44:47]
	v_mfma_f32_16x16x128_f8f6f4 v[36:39], v[16:23], v[222:229], v[36:39]
	v_mfma_f32_16x16x128_f8f6f4 v[32:35], v[24:31], v[222:229], v[32:35]
	s_barrier
	s_add_i32 s61, s61, 2
	s_add_u32 s18, s18, 0x100
	s_addc_u32 s19, s19, 0
	s_add_u32 s59, s59, 0x100
	s_addc_u32 s60, s60, 0
	s_cmp_gt_u32 s61, 13
	s_cbranch_scc0 .LBB0_711
	s_nop 15
	s_nop 15
	s_and_b64 vcc, exec, s[4:5]
	s_cbranch_vccz .LBB0_714
	s_barrier

; __device__ __forceinline__ void xcd_barrier(const XcdBarrier& b) {
;     asm volatile("s_waitcnt vmcnt(0)" ::: "memory");
;     __syncthreads();
;     unsigned xb_z = 0u; asm volatile("" : "+v"(xb_z));
;     if (b.wv == 0 && __builtin_amdgcn_mbcnt_hi(~0u, __builtin_amdgcn_mbcnt_lo(~0u, xb_z)) == 0u) {
;         unsigned* bar = b.bar;
;         __builtin_amdgcn_s_waitcnt(0);
;         unsigned nloc = b.st[0], nx = b.st[1];
;         if (nloc == 0u) { xcd_barrier_complete(bar, b.x, nloc, nx); b.st[0] = nloc; b.st[1] = nx; }
.LBB0_718:
	v_readlane_b32 s0, v254, 30
	s_add_i32 s16, s0, 8
	s_cmp_ge_i32 s16, s83
	s_cbranch_scc1 .LBB0_770
	s_setprio 0
	s_waitcnt vmcnt(0)
	v_readlane_b32 s0, v252, 7
	v_readlane_b32 s1, v252, 8
	v_mov_b32_e32 v0, v129
	s_andn2_b64 vcc, exec, s[0:1]
	s_waitcnt vmcnt(0) lgkmcnt(0)
	s_barrier
	s_cbranch_vccnz .LBB0_769
	v_mbcnt_lo_u32_b32 v0, -1, v0
	v_mbcnt_hi_u32_b32 v0, -1, v0
	v_cmp_eq_u32_e32 vcc, 0, v0
	s_and_saveexec_b64 s[0:1], vcc
	s_cbranch_execz .LBB0_768
	v_mov_b32_e32 v0, s84
	s_waitcnt vmcnt(0) expcnt(0) lgkmcnt(0)
	ds_read_b32 v2, v0
	ds_read_b32 v0, v0 offset:4
	s_waitcnt lgkmcnt(1)
	v_cmp_ne_u32_e32 vcc, 0, v2
	s_cbranch_vccnz .LBB0_736
	s_load_dwordx2 s[2:3], s[90:91], 0x0
	s_load_dword s4, s[90:91], 0x8
	s_mov_b32 s9, 1
	s_waitcnt lgkmcnt(0)
	s_mul_i32 s8, s3, s2
	s_mul_i32 s8, s8, s4
	s_branch .LBB0_724

; __device__ __forceinline__ void xcd_barrier(const XcdBarrier& b) {
;     asm volatile("s_waitcnt vmcnt(0)" ::: "memory");
;     __syncthreads();
;     unsigned xb_z = 0u; asm volatile("" : "+v"(xb_z));
;     if (b.wv == 0 && __builtin_amdgcn_mbcnt_hi(~0u, __builtin_amdgcn_mbcnt_lo(~0u, xb_z)) == 0u) {
;         unsigned* bar = b.bar;
;         __builtin_amdgcn_s_waitcnt(0);
;         unsigned nloc = b.st[0], nx = b.st[1];
;         if (nloc == 0u) { xcd_barrier_complete(bar, b.x, nloc, nx); b.st[0] = nloc; b.st[1] = nx; }
.LBB0_781:
	v_readlane_b32 s0, v254, 30
	s_add_i32 s16, s0, 9
	s_cmp_ge_i32 s16, s83
	s_cbranch_scc1 .LBB0_794
	s_setprio 0
	s_waitcnt vmcnt(0)
	v_readlane_b32 s0, v252, 7
	v_readlane_b32 s1, v252, 8
	v_mov_b32_e32 v0, v129
	s_andn2_b64 vcc, exec, s[0:1]
	s_mov_b32 s17, 0x4a04000
	s_barrier
	s_cbranch_vccnz .LBB0_833
	v_mbcnt_lo_u32_b32 v0, -1, v0
	v_mbcnt_hi_u32_b32 v0, -1, v0
	v_cmp_eq_u32_e32 vcc, 0, v0
	s_and_saveexec_b64 s[0:1], vcc
	s_cbranch_execz .LBB0_832
	v_mov_b32_e32 v0, s84
	s_waitcnt vmcnt(0) expcnt(0) lgkmcnt(0)
	ds_read_b32 v2, v0
	ds_read_b32 v0, v0 offset:4
	s_waitcnt lgkmcnt(1)
	v_cmp_ne_u32_e32 vcc, 0, v2
	s_cbranch_vccnz .LBB0_800
	s_load_dwordx2 s[2:3], s[90:91], 0x0
	s_load_dword s4, s[90:91], 0x8
	s_mov_b32 s9, 1
	s_waitcnt lgkmcnt(0)
	s_mul_i32 s8, s3, s2
	s_mul_i32 s8, s8, s4
	s_branch .LBB0_787

; #define PG8_STAGE(bufoff, gbase, voff) do { _Pragma("unroll") for (int _i = 0; _i < 2; ++_i) \
;         __builtin_amdgcn_global_load_lds((const unsigned*)((const char*)(gbase) + (voff)[_i]), (PG8_LAS unsigned*)(lds + (bufoff) + ldsw + _i * 8192), 16, 0, 0); } while (0)
; #define PG8_LDA(dst, b, h) do { _Pragma("unroll") for (int m = 0; m < 4; ++m) _Pragma("unroll") for (int k = 0; k < 2; ++k) dst[m][k] = *(const PG8_LAS bf16x8*)(lds + PG8_SA(b, h) + aoff + m * 2048 + k * 1024); } while (0)
; #define PG8_LDB(dst, b, h) do { _Pragma("unroll") for (int n = 0; n < 2; ++n) _Pragma("unroll") for (int k = 0; k < 2; ++k) dst[n][k] = *(const PG8_LAS bf16x8*)(lds + (SP2 ? PG8_SB(b, hw) + (h) * 4096 : PG8_SB(b, h)) + boff + n * 2048 + k * 1024); } while (0)
; #define PG8_WAIT_V(n) asm volatile("s_waitcnt vmcnt(" #n ")" ::: "memory")
; #define PG8_WAIT_L(n) asm volatile("s_waitcnt lgkmcnt(" #n ")" ::: "memory")
; #define PG8_BAR __builtin_amdgcn_s_barrier()
; #define PG8_SCHED __builtin_amdgcn_sched_barrier(0)
; template <class Epi, class Sched, bool ALIGN_EPI = false, bool SP2 = false, bool F8 = false>
; __device__ __forceinline__ void gemm_phase(PG8_LAS unsigned char* lds, const Gemm g, const Sched& S, const Epi& E, int wv) {
;     ...
;             const char* a1 = cA + (size_t)(t + 1) * kstep;
;             const char* a2 = last ? nA : cA + (size_t)(t + 2) * kstep; const char* b2 = last ? nB : cB + (size_t)(t + 2) * kstep;
;             const char* a3 = a2 + kstep; const char* b3 = b2 + kstep;
;             if (last && has_next) S.a_ready(nxt);
;             if constexpr (SP2) {
;             PG8_LDB(B0, 0, 0); PG8_LDB(B1, 0, 1); PG8_SCHED; PG8_LDA(At, 0, 0); PG8_STAGE(PG8_SA(1, 1), a1 + hstepA, voffA);
;             PG8_WAIT_V(8); PG8_WAIT_L(0); PG8_BAR; PG8_MMA(0, 0, At, B0); PG8_MMA(0, 1, At, B1); PG8_BAR; PG8_SCHED;
;             PG8_LDA(At, 0, 1); PG8_STAGE(PG8_SB(0, 0), b2, voffB); PG8_STAGE(PG8_SB(0, 1), b2 + hstepB, voffB); PG8_STAGE(PG8_SA(0, 0), a2, voffA);
;             PG8_WAIT_V(8); PG8_WAIT_L(0); PG8_BAR; PG8_MMA(1, 0, At, B0); PG8_MMA(1, 1, At, B1); PG8_BAR; PG8_SCHED;
.LBB0_846:
	v_add_u32_e32 v140, s47, v143
	ds_read_b128 v[146:149], v140
	ds_read_b128 v[150:153], v140 offset:1024
	ds_read_b128 v[154:157], v140 offset:2048
	ds_read_b128 v[158:161], v140 offset:3072
	v_add_u32_e32 v140, s48, v143
	ds_read_b128 v[162:165], v140
	ds_read_b128 v[166:169], v140 offset:1024
	ds_read_b128 v[170:173], v140 offset:2048
	ds_read_b128 v[174:177], v140 offset:3072
	s_add_u32 s22, s20, 0xfff80080
	s_addc_u32 s23, s21, -1
	s_cmp_eq_u32 s61, 28
	s_cselect_b32 s25, s11, s23
	s_cselect_b32 s24, s57, s22
	s_cselect_b32 s23, s9, s60
	s_cselect_b32 s22, s58, s59
	v_lshl_add_u64 v[140:141], s[20:21], 0, v[136:137]
	s_add_i32 m0, s13, 0xc000
	ds_read_b128 v[178:181], v145
	ds_read_b128 v[182:185], v145 offset:1024
	ds_read_b128 v[186:189], v145 offset:2048
	ds_read_b128 v[190:193], v145 offset:3072
	ds_read_b128 v[194:197], v145 offset:4096
	ds_read_b128 v[198:201], v145 offset:5120
	ds_read_b128 v[202:205], v145 offset:6144
	ds_read_b128 v[208:211], v145 offset:7168
	global_load_lds_dwordx4 v[140:141], off
	v_lshl_add_u64 v[140:141], s[20:21], 0, v[138:139]
	s_add_i32 m0, s13, 0xe000
	s_nop 0
	global_load_lds_dwordx4 v[140:141], off
	s_waitcnt vmcnt(8)
	s_waitcnt lgkmcnt(0)
	s_barrier
	s_cmp_lt_u32 s88, 4
	s_cbranch_scc1 .Lprio_lead_5
	s_setprio 1
.Lprio_lead_5:
	s_waitcnt lgkmcnt(0)
	v_mfma_f32_16x16x32_bf16 v[124:127], v[146:149], v[178:181], v[124:127]
	v_mfma_f32_16x16x32_bf16 v[120:123], v[154:157], v[178:181], v[120:123]
	v_mfma_f32_16x16x32_bf16 v[116:119], v[146:149], v[186:189], v[116:119]
	v_mfma_f32_16x16x32_bf16 v[108:111], v[154:157], v[186:189], v[108:111]
	v_mfma_f32_16x16x32_bf16 v[100:103], v[146:149], v[194:197], v[100:103]
	v_mfma_f32_16x16x32_bf16 v[92:95], v[154:157], v[194:197], v[92:95]
	v_mfma_f32_16x16x32_bf16 v[84:87], v[146:149], v[202:205], v[84:87]
	v_mfma_f32_16x16x32_bf16 v[76:79], v[154:157], v[202:205], v[76:79]
	v_mfma_f32_16x16x32_bf16 v[124:127], v[150:153], v[182:185], v[124:127]
	v_mfma_f32_16x16x32_bf16 v[120:123], v[158:161], v[182:185], v[120:123]
	v_mfma_f32_16x16x32_bf16 v[116:119], v[150:153], v[190:193], v[116:119]
	v_mfma_f32_16x16x32_bf16 v[108:111], v[158:161], v[190:193], v[108:111]
	v_mfma_f32_16x16x32_bf16 v[100:103], v[150:153], v[198:201], v[100:103]
	v_mfma_f32_16x16x32_bf16 v[92:95], v[158:161], v[198:201], v[92:95]
	v_mfma_f32_16x16x32_bf16 v[84:87], v[150:153], v[208:211], v[84:87]
	v_mfma_f32_16x16x32_bf16 v[76:79], v[158:161], v[208:211], v[76:79]
	v_mfma_f32_16x16x32_bf16 v[112:115], v[162:165], v[178:181], v[112:115]
	v_mfma_f32_16x16x32_bf16 v[104:107], v[170:173], v[178:181], v[104:107]
	v_mfma_f32_16x16x32_bf16 v[96:99], v[162:165], v[186:189], v[96:99]
	v_mfma_f32_16x16x32_bf16 v[88:91], v[170:173], v[186:189], v[88:91]
	v_mfma_f32_16x16x32_bf16 v[80:83], v[162:165], v[194:197], v[80:83]
	v_mfma_f32_16x16x32_bf16 v[72:75], v[170:173], v[194:197], v[72:75]
	v_mfma_f32_16x16x32_bf16 v[68:71], v[162:165], v[202:205], v[68:71]
	v_mfma_f32_16x16x32_bf16 v[64:67], v[170:173], v[202:205], v[64:67]
	v_mfma_f32_16x16x32_bf16 v[112:115], v[166:169], v[182:185], v[112:115]
	v_mfma_f32_16x16x32_bf16 v[104:107], v[174:177], v[182:185], v[104:107]
	v_mfma_f32_16x16x32_bf16 v[96:99], v[166:169], v[190:193], v[96:99]
	v_mfma_f32_16x16x32_bf16 v[88:91], v[174:177], v[190:193], v[88:91]
	v_mfma_f32_16x16x32_bf16 v[80:83], v[166:169], v[198:201], v[80:83]
	v_mfma_f32_16x16x32_bf16 v[72:75], v[174:177], v[198:201], v[72:75]
	v_mfma_f32_16x16x32_bf16 v[68:71], v[166:169], v[208:211], v[68:71]
	v_mfma_f32_16x16x32_bf16 v[64:67], v[174:177], v[208:211], v[64:67]
	s_barrier
	s_mov_b32 m0, s15
	v_lshl_add_u64 v[140:141], s[22:23], 0, v[128:129]
	s_add_u32 s62, s22, 0x80000
	ds_read_b128 v[178:181], v145 offset:16384
	ds_read_b128 v[182:185], v145 offset:17408
	ds_read_b128 v[186:189], v145 offset:18432
	ds_read_b128 v[190:193], v145 offset:19456
	ds_read_b128 v[194:197], v145 offset:20480
	ds_read_b128 v[198:201], v145 offset:21504
	ds_read_b128 v[202:205], v145 offset:22528
	ds_read_b128 v[208:211], v145 offset:23552
	global_load_lds_dwordx4 v[140:141], off
	v_lshl_add_u64 v[214:215], s[22:23], 0, v[130:131]
	s_mov_b32 m0, s34
	s_addc_u32 s63, s23, 0
	global_load_lds_dwordx4 v[214:215], off
	v_lshl_add_u64 v[216:217], s[62:63], 0, v[128:129]
	s_mov_b32 m0, s35
	v_lshl_add_u64 v[218:219], s[24:25], 0, v[132:133]
	global_load_lds_dwordx4 v[216:217], off
	v_lshl_add_u64 v[216:217], s[62:63], 0, v[130:131]
	s_mov_b32 m0, s36
	s_nop 0
	global_load_lds_dwordx4 v[216:217], off
	v_lshl_add_u64 v[216:217], s[24:25], 0, v[134:135]
	s_mov_b32 m0, s13
	s_nop 0
	global_load_lds_dwordx4 v[216:217], off
	s_mov_b32 m0, s37
	s_nop 0
	global_load_lds_dwordx4 v[218:219], off
	s_waitcnt vmcnt(8)
	s_waitcnt lgkmcnt(0)
	s_barrier
; #define PG8_STAGE(bufoff, gbase, voff) do { _Pragma("unroll") for (int _i = 0; _i < 2; ++_i) \
;         __builtin_amdgcn_global_load_lds((const unsigned*)((const char*)(gbase) + (voff)[_i]), (PG8_LAS unsigned*)(lds + (bufoff) + ldsw + _i * 8192), 16, 0, 0); } while (0)
; #define PG8_LDA(dst, b, h) do { _Pragma("unroll") for (int m = 0; m < 4; ++m) _Pragma("unroll") for (int k = 0; k < 2; ++k) dst[m][k] = *(const PG8_LAS bf16x8*)(lds + PG8_SA(b, h) + aoff + m * 2048 + k * 1024); } while (0)
; #define PG8_LDB(dst, b, h) do { _Pragma("unroll") for (int n = 0; n < 2; ++n) _Pragma("unroll") for (int k = 0; k < 2; ++k) dst[n][k] = *(const PG8_LAS bf16x8*)(lds + (SP2 ? PG8_SB(b, hw) + (h) * 4096 : PG8_SB(b, h)) + boff + n * 2048 + k * 1024); } while (0)
; #define PG8_WAIT_V(n) asm volatile("s_waitcnt vmcnt(" #n ")" ::: "memory")
; #define PG8_WAIT_L(n) asm volatile("s_waitcnt lgkmcnt(" #n ")" ::: "memory")
; #define PG8_BAR __builtin_amdgcn_s_barrier()
; #define PG8_SCHED __builtin_amdgcn_sched_barrier(0)
; template <class Epi, class Sched, bool ALIGN_EPI = false, bool SP2 = false, bool F8 = false>
; __device__ __forceinline__ void gemm_phase(PG8_LAS unsigned char* lds, const Gemm g, const Sched& S, const Epi& E, int wv) {
;     ...
;             PG8_WAIT_V(8); PG8_WAIT_L(0); PG8_BAR; PG8_MMA(1, 0, At, B0); PG8_MMA(1, 1, At, B1); PG8_BAR; PG8_SCHED;
;             PG8_LDB(B0, 1, 0); PG8_LDB(B1, 1, 1); PG8_SCHED; PG8_LDA(At, 1, 0); PG8_STAGE(PG8_SA(0, 1), a2 + hstepA, voffA);
;             PG8_WAIT_V(8); PG8_WAIT_L(0); PG8_BAR; PG8_MMA(0, 0, At, B0); PG8_MMA(0, 1, At, B1); PG8_BAR; PG8_SCHED;
	s_waitcnt lgkmcnt(0)
	v_mfma_f32_16x16x32_bf16 v[60:63], v[146:149], v[178:181], v[60:63]
	v_mfma_f32_16x16x32_bf16 v[56:59], v[154:157], v[178:181], v[56:59]
	v_mfma_f32_16x16x32_bf16 v[52:55], v[146:149], v[186:189], v[52:55]
	v_mfma_f32_16x16x32_bf16 v[44:47], v[154:157], v[186:189], v[44:47]
	v_mfma_f32_16x16x32_bf16 v[36:39], v[146:149], v[194:197], v[36:39]
	v_mfma_f32_16x16x32_bf16 v[28:31], v[154:157], v[194:197], v[28:31]
	v_mfma_f32_16x16x32_bf16 v[20:23], v[146:149], v[202:205], v[20:23]
	v_mfma_f32_16x16x32_bf16 v[12:15], v[154:157], v[202:205], v[12:15]
	v_mfma_f32_16x16x32_bf16 v[60:63], v[150:153], v[182:185], v[60:63]
	v_mfma_f32_16x16x32_bf16 v[56:59], v[158:161], v[182:185], v[56:59]
	v_mfma_f32_16x16x32_bf16 v[52:55], v[150:153], v[190:193], v[52:55]
	v_mfma_f32_16x16x32_bf16 v[44:47], v[158:161], v[190:193], v[44:47]
	v_mfma_f32_16x16x32_bf16 v[36:39], v[150:153], v[198:201], v[36:39]
	v_mfma_f32_16x16x32_bf16 v[28:31], v[158:161], v[198:201], v[28:31]
	v_mfma_f32_16x16x32_bf16 v[20:23], v[150:153], v[208:211], v[20:23]
	v_mfma_f32_16x16x32_bf16 v[12:15], v[158:161], v[208:211], v[12:15]
	v_mfma_f32_16x16x32_bf16 v[48:51], v[162:165], v[178:181], v[48:51]
	v_mfma_f32_16x16x32_bf16 v[40:43], v[170:173], v[178:181], v[40:43]
	v_mfma_f32_16x16x32_bf16 v[32:35], v[162:165], v[186:189], v[32:35]
	v_mfma_f32_16x16x32_bf16 v[24:27], v[170:173], v[186:189], v[24:27]
	v_mfma_f32_16x16x32_bf16 v[16:19], v[162:165], v[194:197], v[16:19]
	v_mfma_f32_16x16x32_bf16 v[8:11], v[170:173], v[194:197], v[8:11]
	v_mfma_f32_16x16x32_bf16 v[4:7], v[162:165], v[202:205], v[4:7]
	v_mfma_f32_16x16x32_bf16 v[0:3], v[170:173], v[202:205], v[0:3]
	v_mfma_f32_16x16x32_bf16 v[48:51], v[166:169], v[182:185], v[48:51]
	v_mfma_f32_16x16x32_bf16 v[40:43], v[174:177], v[182:185], v[40:43]
	v_mfma_f32_16x16x32_bf16 v[32:35], v[166:169], v[190:193], v[32:35]
	v_mfma_f32_16x16x32_bf16 v[24:27], v[174:177], v[190:193], v[24:27]
	v_mfma_f32_16x16x32_bf16 v[16:19], v[166:169], v[198:201], v[16:19]
	v_mfma_f32_16x16x32_bf16 v[8:11], v[174:177], v[198:201], v[8:11]
	v_mfma_f32_16x16x32_bf16 v[4:7], v[166:169], v[208:211], v[4:7]
	v_mfma_f32_16x16x32_bf16 v[0:3], v[174:177], v[208:211], v[0:3]
	s_barrier
	v_add_u32_e32 v158, s49, v143
	v_add_u32_e32 v174, s54, v143
	ds_read_b128 v[146:149], v158
	ds_read_b128 v[150:153], v158 offset:1024
	ds_read_b128 v[154:157], v158 offset:2048
	ds_read_b128 v[158:161], v158 offset:3072
	ds_read_b128 v[162:165], v174
	ds_read_b128 v[166:169], v174 offset:1024
	ds_read_b128 v[170:173], v174 offset:2048
	ds_read_b128 v[174:177], v174 offset:3072
	s_add_u32 s24, s24, 0x80000
	s_addc_u32 s25, s25, 0
	s_mov_b32 m0, s38
	v_lshl_add_u64 v[220:221], s[24:25], 0, v[134:135]
	ds_read_b128 v[178:181], v145 offset:32768
	ds_read_b128 v[182:185], v145 offset:33792
	ds_read_b128 v[186:189], v145 offset:34816
	ds_read_b128 v[190:193], v145 offset:35840
	ds_read_b128 v[194:197], v145 offset:36864
	ds_read_b128 v[198:201], v145 offset:37888
	ds_read_b128 v[202:205], v145 offset:38912
	ds_read_b128 v[208:211], v145 offset:39936
	global_load_lds_dwordx4 v[220:221], off
	v_lshl_add_u64 v[220:221], s[24:25], 0, v[132:133]
	s_mov_b32 m0, s39
	s_nop 0
	global_load_lds_dwordx4 v[220:221], off
	s_waitcnt vmcnt(8)
	s_waitcnt lgkmcnt(0)
	s_barrier
	s_waitcnt lgkmcnt(0)
	v_mfma_f32_16x16x32_bf16 v[124:127], v[146:149], v[178:181], v[124:127]
	v_mfma_f32_16x16x32_bf16 v[120:123], v[154:157], v[178:181], v[120:123]
	v_mfma_f32_16x16x32_bf16 v[116:119], v[146:149], v[186:189], v[116:119]
	v_mfma_f32_16x16x32_bf16 v[108:111], v[154:157], v[186:189], v[108:111]
	v_mfma_f32_16x16x32_bf16 v[100:103], v[146:149], v[194:197], v[100:103]
	v_mfma_f32_16x16x32_bf16 v[92:95], v[154:157], v[194:197], v[92:95]
	v_mfma_f32_16x16x32_bf16 v[84:87], v[146:149], v[202:205], v[84:87]
	v_mfma_f32_16x16x32_bf16 v[76:79], v[154:157], v[202:205], v[76:79]
	v_mfma_f32_16x16x32_bf16 v[124:127], v[150:153], v[182:185], v[124:127]
	v_mfma_f32_16x16x32_bf16 v[120:123], v[158:161], v[182:185], v[120:123]
	v_mfma_f32_16x16x32_bf16 v[116:119], v[150:153], v[190:193], v[116:119]
	v_mfma_f32_16x16x32_bf16 v[108:111], v[158:161], v[190:193], v[108:111]
	v_mfma_f32_16x16x32_bf16 v[100:103], v[150:153], v[198:201], v[100:103]
	v_mfma_f32_16x16x32_bf16 v[92:95], v[158:161], v[198:201], v[92:95]
	v_mfma_f32_16x16x32_bf16 v[84:87], v[150:153], v[208:211], v[84:87]
	v_mfma_f32_16x16x32_bf16 v[76:79], v[158:161], v[208:211], v[76:79]
	v_mfma_f32_16x16x32_bf16 v[112:115], v[162:165], v[178:181], v[112:115]
	v_mfma_f32_16x16x32_bf16 v[104:107], v[170:173], v[178:181], v[104:107]
	v_mfma_f32_16x16x32_bf16 v[96:99], v[162:165], v[186:189], v[96:99]
	v_mfma_f32_16x16x32_bf16 v[88:91], v[170:173], v[186:189], v[88:91]
	v_mfma_f32_16x16x32_bf16 v[80:83], v[162:165], v[194:197], v[80:83]
	v_mfma_f32_16x16x32_bf16 v[72:75], v[170:173], v[194:197], v[72:75]
	v_mfma_f32_16x16x32_bf16 v[68:71], v[162:165], v[202:205], v[68:71]
	v_mfma_f32_16x16x32_bf16 v[64:67], v[170:173], v[202:205], v[64:67]
	v_mfma_f32_16x16x32_bf16 v[112:115], v[166:169], v[182:185], v[112:115]
	v_mfma_f32_16x16x32_bf16 v[104:107], v[174:177], v[182:185], v[104:107]
	v_mfma_f32_16x16x32_bf16 v[96:99], v[166:169], v[190:193], v[96:99]
	v_mfma_f32_16x16x32_bf16 v[88:91], v[174:177], v[190:193], v[88:91]
	v_mfma_f32_16x16x32_bf16 v[80:83], v[166:169], v[198:201], v[80:83]
	v_mfma_f32_16x16x32_bf16 v[72:75], v[174:177], v[198:201], v[72:75]
	v_mfma_f32_16x16x32_bf16 v[68:71], v[166:169], v[208:211], v[68:71]
	v_mfma_f32_16x16x32_bf16 v[64:67], v[174:177], v[208:211], v[64:67]
	s_barrier
; #define PG8_STAGE(bufoff, gbase, voff) do { _Pragma("unroll") for (int _i = 0; _i < 2; ++_i) \
;         __builtin_amdgcn_global_load_lds((const unsigned*)((const char*)(gbase) + (voff)[_i]), (PG8_LAS unsigned*)(lds + (bufoff) + ldsw + _i * 8192), 16, 0, 0); } while (0)
; #define PG8_LDA(dst, b, h) do { _Pragma("unroll") for (int m = 0; m < 4; ++m) _Pragma("unroll") for (int k = 0; k < 2; ++k) dst[m][k] = *(const PG8_LAS bf16x8*)(lds + PG8_SA(b, h) + aoff + m * 2048 + k * 1024); } while (0)
; #define PG8_WAIT_V(n) asm volatile("s_waitcnt vmcnt(" #n ")" ::: "memory")
; #define PG8_WAIT_L(n) asm volatile("s_waitcnt lgkmcnt(" #n ")" ::: "memory")
; #define PG8_BAR __builtin_amdgcn_s_barrier()
; #define PG8_SCHED __builtin_amdgcn_sched_barrier(0)
; template <class Epi, class Sched, bool ALIGN_EPI = false, bool SP2 = false, bool F8 = false>
; __device__ __forceinline__ void gemm_phase(PG8_LAS unsigned char* lds, const Gemm g, const Sched& S, const Epi& E, int wv) {
;     ...
;             PG8_LDA(At, 1, 1); PG8_STAGE(PG8_SB(1, 0), b3, voffB); PG8_STAGE(PG8_SB(1, 1), b3 + hstepB, voffB); PG8_STAGE(PG8_SA(1, 0), a3, voffA);
;             PG8_WAIT_V(8); PG8_WAIT_L(0); PG8_BAR; PG8_MMA(1, 0, At, B0); PG8_MMA(1, 1, At, B1); PG8_BAR; PG8_SCHED;
	s_mov_b32 m0, s41
	v_lshl_add_u64 v[140:141], v[140:141], 0, s[52:53]
	s_add_u32 s22, s22, 0x80080
	ds_read_b128 v[178:181], v145 offset:49152
	ds_read_b128 v[182:185], v145 offset:50176
	ds_read_b128 v[186:189], v145 offset:51200
	ds_read_b128 v[190:193], v145 offset:52224
	ds_read_b128 v[194:197], v145 offset:53248
	ds_read_b128 v[198:201], v145 offset:54272
	ds_read_b128 v[202:205], v145 offset:55296
	ds_read_b128 v[208:211], v145 offset:56320
	global_load_lds_dwordx4 v[140:141], off
	v_lshl_add_u64 v[140:141], v[214:215], 0, s[52:53]
	s_mov_b32 m0, s42
	s_addc_u32 s23, s23, 0
	global_load_lds_dwordx4 v[140:141], off
	v_lshl_add_u64 v[140:141], s[22:23], 0, v[128:129]
	s_mov_b32 m0, s45
	s_nop 0
	global_load_lds_dwordx4 v[140:141], off
	v_lshl_add_u64 v[140:141], s[22:23], 0, v[130:131]
	s_mov_b32 m0, s46
	s_nop 0
	global_load_lds_dwordx4 v[140:141], off
	v_lshl_add_u64 v[140:141], v[216:217], 0, s[52:53]
	s_mov_b32 m0, s43
	s_nop 0
	global_load_lds_dwordx4 v[140:141], off
	v_lshl_add_u64 v[140:141], v[218:219], 0, s[52:53]
	s_mov_b32 m0, s44
	s_nop 0
	global_load_lds_dwordx4 v[140:141], off
	s_waitcnt vmcnt(8)
	s_waitcnt lgkmcnt(0)
	s_barrier
	s_waitcnt lgkmcnt(0)
	v_mfma_f32_16x16x32_bf16 v[60:63], v[146:149], v[178:181], v[60:63]
	v_mfma_f32_16x16x32_bf16 v[56:59], v[154:157], v[178:181], v[56:59]
	v_mfma_f32_16x16x32_bf16 v[52:55], v[146:149], v[186:189], v[52:55]
	v_mfma_f32_16x16x32_bf16 v[44:47], v[154:157], v[186:189], v[44:47]
	v_mfma_f32_16x16x32_bf16 v[36:39], v[146:149], v[194:197], v[36:39]
	v_mfma_f32_16x16x32_bf16 v[28:31], v[154:157], v[194:197], v[28:31]
	v_mfma_f32_16x16x32_bf16 v[20:23], v[146:149], v[202:205], v[20:23]
	v_mfma_f32_16x16x32_bf16 v[12:15], v[154:157], v[202:205], v[12:15]
	v_mfma_f32_16x16x32_bf16 v[60:63], v[150:153], v[182:185], v[60:63]
	v_mfma_f32_16x16x32_bf16 v[56:59], v[158:161], v[182:185], v[56:59]
	v_mfma_f32_16x16x32_bf16 v[52:55], v[150:153], v[190:193], v[52:55]
	v_mfma_f32_16x16x32_bf16 v[44:47], v[158:161], v[190:193], v[44:47]
	v_mfma_f32_16x16x32_bf16 v[36:39], v[150:153], v[198:201], v[36:39]
	v_mfma_f32_16x16x32_bf16 v[28:31], v[158:161], v[198:201], v[28:31]
	v_mfma_f32_16x16x32_bf16 v[20:23], v[150:153], v[208:211], v[20:23]
	v_mfma_f32_16x16x32_bf16 v[12:15], v[158:161], v[208:211], v[12:15]
	v_mfma_f32_16x16x32_bf16 v[48:51], v[162:165], v[178:181], v[48:51]
	v_mfma_f32_16x16x32_bf16 v[40:43], v[170:173], v[178:181], v[40:43]
	v_mfma_f32_16x16x32_bf16 v[32:35], v[162:165], v[186:189], v[32:35]
	v_mfma_f32_16x16x32_bf16 v[24:27], v[170:173], v[186:189], v[24:27]
	v_mfma_f32_16x16x32_bf16 v[16:19], v[162:165], v[194:197], v[16:19]
	v_mfma_f32_16x16x32_bf16 v[8:11], v[170:173], v[194:197], v[8:11]
	v_mfma_f32_16x16x32_bf16 v[4:7], v[162:165], v[202:205], v[4:7]
	v_mfma_f32_16x16x32_bf16 v[0:3], v[170:173], v[202:205], v[0:3]
	v_mfma_f32_16x16x32_bf16 v[48:51], v[166:169], v[182:185], v[48:51]
	v_mfma_f32_16x16x32_bf16 v[40:43], v[174:177], v[182:185], v[40:43]
	v_mfma_f32_16x16x32_bf16 v[32:35], v[166:169], v[190:193], v[32:35]
	v_mfma_f32_16x16x32_bf16 v[24:27], v[174:177], v[190:193], v[24:27]
	v_mfma_f32_16x16x32_bf16 v[16:19], v[166:169], v[198:201], v[16:19]
	v_mfma_f32_16x16x32_bf16 v[8:11], v[174:177], v[198:201], v[8:11]
	v_mfma_f32_16x16x32_bf16 v[4:7], v[166:169], v[208:211], v[4:7]
	v_mfma_f32_16x16x32_bf16 v[0:3], v[174:177], v[208:211], v[0:3]
	s_barrier
	s_add_i32 s61, s61, 2
	s_add_u32 s20, s20, 0x100
	s_addc_u32 s21, s21, 0
	s_add_u32 s59, s59, 0x100
	s_addc_u32 s60, s60, 0
	s_cmp_gt_u32 s61, 29
	s_cbranch_scc0 .LBB0_846
	s_and_b64 vcc, exec, s[6:7]
	s_cbranch_vccz .LBB0_849
	s_barrier

; __device__ __forceinline__ void xcd_barrier(const XcdBarrier& b) {
;     asm volatile("s_waitcnt vmcnt(0)" ::: "memory");
;     __syncthreads();
;     unsigned xb_z = 0u; asm volatile("" : "+v"(xb_z));
;     if (b.wv == 0 && __builtin_amdgcn_mbcnt_hi(~0u, __builtin_amdgcn_mbcnt_lo(~0u, xb_z)) == 0u) {
;         unsigned* bar = b.bar;
;         __builtin_amdgcn_s_waitcnt(0);
;         unsigned nloc = b.st[0], nx = b.st[1];
;         if (nloc == 0u) { xcd_barrier_complete(bar, b.x, nloc, nx); b.st[0] = nloc; b.st[1] = nx; }
.LBB0_853:
	v_readlane_b32 s0, v254, 30
	s_add_i32 s16, s0, 10
	s_cmp_ge_i32 s16, s83
	s_cbranch_scc1 .LBB0_905
	s_setprio 0
	s_waitcnt vmcnt(0)
	v_readlane_b32 s0, v252, 7
	v_readlane_b32 s1, v252, 8
	v_mov_b32_e32 v0, v129
	s_andn2_b64 vcc, exec, s[0:1]
	s_waitcnt vmcnt(0) lgkmcnt(0)
	s_barrier
	s_cbranch_vccnz .LBB0_904
	v_mbcnt_lo_u32_b32 v0, -1, v0
	v_mbcnt_hi_u32_b32 v0, -1, v0
	v_cmp_eq_u32_e32 vcc, 0, v0
	s_and_saveexec_b64 s[0:1], vcc
	s_cbranch_execz .LBB0_903
	v_mov_b32_e32 v0, s84
	s_waitcnt vmcnt(0) expcnt(0) lgkmcnt(0)
	ds_read_b32 v2, v0
	ds_read_b32 v0, v0 offset:4
	s_waitcnt lgkmcnt(1)
	v_cmp_ne_u32_e32 vcc, 0, v2
	s_cbranch_vccnz .LBB0_871
	s_load_dwordx2 s[2:3], s[90:91], 0x0
	s_load_dword s4, s[90:91], 0x8
	s_mov_b32 s9, 1
	s_waitcnt lgkmcnt(0)
	s_mul_i32 s8, s3, s2
	s_mul_i32 s8, s8, s4
	s_branch .LBB0_859

; __device__ __forceinline__ void xcd_barrier(const XcdBarrier& b) {
;     asm volatile("s_waitcnt vmcnt(0)" ::: "memory");
;     __syncthreads();
;     unsigned xb_z = 0u; asm volatile("" : "+v"(xb_z));
;     if (b.wv == 0 && __builtin_amdgcn_mbcnt_hi(~0u, __builtin_amdgcn_mbcnt_lo(~0u, xb_z)) == 0u) {
;         unsigned* bar = b.bar;
;         __builtin_amdgcn_s_waitcnt(0);
;         unsigned nloc = b.st[0], nx = b.st[1];
;         if (nloc == 0u) { xcd_barrier_complete(bar, b.x, nloc, nx); b.st[0] = nloc; b.st[1] = nx; }
.LBB0_921:
	v_readlane_b32 s0, v254, 30
	s_add_i32 s16, s0, 11
	s_cmp_ge_i32 s16, s83
	s_cbranch_scc1 .LBB0_934
	s_setprio 0
	s_waitcnt vmcnt(0)
	v_readlane_b32 s0, v252, 7
	v_readlane_b32 s1, v252, 8
	v_mov_b32_e32 v0, v129
	s_andn2_b64 vcc, exec, s[0:1]
	v_readlane_b32 s15, v254, 35
	s_waitcnt lgkmcnt(0)
	s_barrier
	s_cbranch_vccnz .LBB0_973
	v_mbcnt_lo_u32_b32 v0, -1, v0
	v_mbcnt_hi_u32_b32 v0, -1, v0
	v_cmp_eq_u32_e32 vcc, 0, v0
	s_and_saveexec_b64 s[0:1], vcc
	s_cbranch_execz .LBB0_972
	v_mov_b32_e32 v0, s84
	s_waitcnt vmcnt(0) expcnt(0) lgkmcnt(0)
	ds_read_b32 v2, v0
	ds_read_b32 v0, v0 offset:4
	s_waitcnt lgkmcnt(1)
	v_cmp_ne_u32_e32 vcc, 0, v2
	s_cbranch_vccnz .LBB0_940
	s_load_dwordx2 s[2:3], s[90:91], 0x0
	s_load_dword s4, s[90:91], 0x8
	s_mov_b32 s9, 1
	s_waitcnt lgkmcnt(0)
	s_mul_i32 s8, s3, s2
	s_mul_i32 s8, s8, s4
	s_branch .LBB0_927

; __device__ __forceinline__ void xcd_barrier(const XcdBarrier& b) {
;     asm volatile("s_waitcnt vmcnt(0)" ::: "memory");
;     __syncthreads();
;     unsigned xb_z = 0u; asm volatile("" : "+v"(xb_z));
;     if (b.wv == 0 && __builtin_amdgcn_mbcnt_hi(~0u, __builtin_amdgcn_mbcnt_lo(~0u, xb_z)) == 0u) {
;         unsigned* bar = b.bar;
;         __builtin_amdgcn_s_waitcnt(0);
;         unsigned nloc = b.st[0], nx = b.st[1];
;         if (nloc == 0u) { xcd_barrier_complete(bar, b.x, nloc, nx); b.st[0] = nloc; b.st[1] = nx; }
.LBB0_980:
	v_readlane_b32 s0, v254, 30
	s_add_i32 s16, s0, 12
	s_cmp_ge_i32 s16, s83
	s_cbranch_scc1 .LBB0_1032
	s_setprio 0
	s_waitcnt vmcnt(0)
	v_readlane_b32 s0, v252, 7
	v_readlane_b32 s1, v252, 8
	v_mov_b32_e32 v0, v129
	s_andn2_b64 vcc, exec, s[0:1]
	s_barrier
	s_cbranch_vccnz .LBB0_1031
	v_mbcnt_lo_u32_b32 v0, -1, v0
	v_mbcnt_hi_u32_b32 v0, -1, v0
	v_cmp_eq_u32_e32 vcc, 0, v0
	s_and_saveexec_b64 s[0:1], vcc
	s_cbranch_execz .LBB0_1030
	v_mov_b32_e32 v0, s84
	s_waitcnt vmcnt(0) expcnt(0) lgkmcnt(0)
	ds_read_b32 v2, v0
	ds_read_b32 v0, v0 offset:4
	s_waitcnt lgkmcnt(1)
	v_cmp_ne_u32_e32 vcc, 0, v2
	s_cbranch_vccnz .LBB0_998
	s_load_dwordx2 s[2:3], s[90:91], 0x0
	s_load_dword s4, s[90:91], 0x8
	s_mov_b32 s9, 1
	s_waitcnt lgkmcnt(0)
	s_mul_i32 s8, s3, s2
	s_mul_i32 s8, s8, s4
	s_branch .LBB0_986

; __device__ __forceinline__ void xcd_barrier(const XcdBarrier& b) {
;     asm volatile("s_waitcnt vmcnt(0)" ::: "memory");
;     __syncthreads();
;     unsigned xb_z = 0u; asm volatile("" : "+v"(xb_z));
;     if (b.wv == 0 && __builtin_amdgcn_mbcnt_hi(~0u, __builtin_amdgcn_mbcnt_lo(~0u, xb_z)) == 0u) {
;         unsigned* bar = b.bar;
;         __builtin_amdgcn_s_waitcnt(0);
;         unsigned nloc = b.st[0], nx = b.st[1];
;         if (nloc == 0u) { xcd_barrier_complete(bar, b.x, nloc, nx); b.st[0] = nloc; b.st[1] = nx; }
.LBB0_1038:
	s_or_b64 exec, exec, s[8:9]
	v_readlane_b32 s0, v254, 30
	s_add_i32 s16, s0, 13
	s_cmp_ge_i32 s16, s83
	s_cbranch_scc1 .LBB0_1090
	s_setprio 0
	s_waitcnt vmcnt(0)
	v_readlane_b32 s0, v252, 7
	v_readlane_b32 s1, v252, 8
	v_mov_b32_e32 v0, v129
	s_andn2_b64 vcc, exec, s[0:1]
	s_barrier
	s_cbranch_vccnz .LBB0_1089
	v_mbcnt_lo_u32_b32 v0, -1, v0
	v_mbcnt_hi_u32_b32 v0, -1, v0
	v_cmp_eq_u32_e32 vcc, 0, v0
	s_and_saveexec_b64 s[0:1], vcc
	s_cbranch_execz .LBB0_1088
	v_mov_b32_e32 v0, s84
	s_waitcnt vmcnt(0) expcnt(0) lgkmcnt(0)
	ds_read_b32 v2, v0
	ds_read_b32 v0, v0 offset:4
	s_waitcnt lgkmcnt(1)
	v_cmp_ne_u32_e32 vcc, 0, v2
	s_cbranch_vccnz .LBB0_1056
	s_load_dwordx2 s[2:3], s[90:91], 0x0
	s_load_dword s4, s[90:91], 0x8
	s_mov_b32 s9, 1
	s_waitcnt lgkmcnt(0)
	s_mul_i32 s8, s3, s2
	s_mul_i32 s8, s8, s4
	s_branch .LBB0_1044

; __device__ __forceinline__ void xcd_barrier(const XcdBarrier& b) {
;     asm volatile("s_waitcnt vmcnt(0)" ::: "memory");
;     __syncthreads();
;     unsigned xb_z = 0u; asm volatile("" : "+v"(xb_z));
;     if (b.wv == 0 && __builtin_amdgcn_mbcnt_hi(~0u, __builtin_amdgcn_mbcnt_lo(~0u, xb_z)) == 0u) {
;         unsigned* bar = b.bar;
;         __builtin_amdgcn_s_waitcnt(0);
;         unsigned nloc = b.st[0], nx = b.st[1];
;         if (nloc == 0u) { xcd_barrier_complete(bar, b.x, nloc, nx); b.st[0] = nloc; b.st[1] = nx; }
.LBB0_1096:
	s_or_b64 exec, exec, s[6:7]
	v_readlane_b32 s0, v254, 30
	s_add_i32 s16, s0, 14
	s_cmp_ge_i32 s16, s83
	s_cbranch_scc1 .LBB0_1148
	s_setprio 0
	s_waitcnt vmcnt(0)
	v_readlane_b32 s0, v252, 7
	v_readlane_b32 s1, v252, 8
	v_mov_b32_e32 v0, v129
	s_andn2_b64 vcc, exec, s[0:1]
	s_barrier
	s_cbranch_vccnz .LBB0_1147
	v_mbcnt_lo_u32_b32 v0, -1, v0
	v_mbcnt_hi_u32_b32 v0, -1, v0
	v_cmp_eq_u32_e32 vcc, 0, v0
	s_and_saveexec_b64 s[0:1], vcc
	s_cbranch_execz .LBB0_1146
	v_mov_b32_e32 v0, s84
	s_waitcnt vmcnt(0) expcnt(0) lgkmcnt(0)
	ds_read_b32 v2, v0
	ds_read_b32 v0, v0 offset:4
	s_waitcnt lgkmcnt(1)
	v_cmp_ne_u32_e32 vcc, 0, v2
	s_cbranch_vccnz .LBB0_1114
	s_load_dwordx2 s[2:3], s[90:91], 0x0
	s_load_dword s4, s[90:91], 0x8
	s_mov_b32 s9, 1
	s_waitcnt lgkmcnt(0)
	s_mul_i32 s8, s3, s2
	s_mul_i32 s8, s8, s4
	s_branch .LBB0_1102

; __device__ __forceinline__ void xcd_barrier(const XcdBarrier& b) {
;     asm volatile("s_waitcnt vmcnt(0)" ::: "memory");
;     __syncthreads();
;     unsigned xb_z = 0u; asm volatile("" : "+v"(xb_z));
;     if (b.wv == 0 && __builtin_amdgcn_mbcnt_hi(~0u, __builtin_amdgcn_mbcnt_lo(~0u, xb_z)) == 0u) {
.LBB0_1155:
	s_setprio 0
	s_waitcnt vmcnt(0)
	v_readlane_b32 s0, v252, 7
	v_readlane_b32 s1, v252, 8
	v_mov_b32_e32 v0, v129
	s_andn2_b64 vcc, exec, s[0:1]
	s_barrier
	s_cbranch_vccz .LBB0_1156
	s_getpc_b64 s[98:99]
